# K-loops: vmcnt and lgkmcnt waits before the publish barrier merged into one s_waitcnt (24 sites)
# baseline (speedup 1.0000x reference)
.LBB0_211:
	s_ashr_i32 s17, s16, 31
	s_lshl_b64 s[18:19], s[16:17], 19
	s_add_u32 s18, s68, s18
	s_addc_u32 s19, s69, s19
	s_and_b64 s[20:21], s[0:1], exec
	s_cselect_b32 s17, s19, s25
	s_cselect_b32 s44, s18, s24
	s_ashr_i32 s15, s14, 31
	s_lshl_b64 s[20:21], s[14:15], 19
	s_add_u32 s20, s3, s20
	s_addc_u32 s21, s6, s21
	s_and_b64 s[28:29], s[0:1], exec
	s_cselect_b32 s15, s21, s27
	s_cselect_b32 s45, s20, s26
	s_add_u32 s24, s24, 0x40080
	s_addc_u32 s25, s25, 0
	s_add_u32 s46, s26, 0x100
	s_addc_u32 s47, s27, 0
	s_mov_b32 s70, -2
	ds_read_b128 v[146:149], v153
	ds_read_b128 v[156:159], v153 offset:1024
	ds_read_b128 v[160:163], v153 offset:2048
	ds_read_b128 v[164:167], v153 offset:3072
	ds_read_b128 v[174:177], v154
	ds_read_b128 v[178:181], v154 offset:1024
	ds_read_b128 v[182:185], v154 offset:2048
	ds_read_b128 v[186:189], v154 offset:3072
	s_add_u32 s26, s24, 0xfffc0080
	s_addc_u32 s27, s25, -1
	s_cmp_eq_u32 s70, 12
	s_cselect_b32 s29, s17, s27
	s_cselect_b32 s28, s44, s26
	s_cselect_b32 s27, s15, s47
	s_cselect_b32 s26, s45, s46
	s_add_i32 m0, s23, 0xc000
	ds_read_b128 v[190:193], v155
	ds_read_b128 v[194:197], v155 offset:1024
	ds_read_b128 v[198:201], v155 offset:2048
	ds_read_b128 v[202:205], v155 offset:3072
	ds_read_b128 v[206:209], v155 offset:4096
	ds_read_b128 v[210:213], v155 offset:5120
	ds_read_b128 v[214:217], v155 offset:6144
	ds_read_b128 v[218:221], v155 offset:7168
	global_load_lds_dwordx4 v138, s[24:25]
	s_add_i32 m0, s23, 0xe000
	s_nop 0
	global_load_lds_dwordx4 v140, s[24:25]
	s_waitcnt vmcnt(8) lgkmcnt(0)
	s_barrier
	v_mfma_f32_16x16x32_bf16 v[126:129], v[146:149], v[190:193], 0
	v_mfma_f32_16x16x32_bf16 v[122:125], v[160:163], v[190:193], 0
	v_mfma_f32_16x16x32_bf16 v[118:121], v[146:149], v[198:201], 0
	v_mfma_f32_16x16x32_bf16 v[110:113], v[160:163], v[198:201], 0
	v_mfma_f32_16x16x32_bf16 v[102:105], v[146:149], v[206:209], 0
	v_mfma_f32_16x16x32_bf16 v[94:97], v[160:163], v[206:209], 0
	v_mfma_f32_16x16x32_bf16 v[86:89], v[146:149], v[214:217], 0
	v_mfma_f32_16x16x32_bf16 v[78:81], v[160:163], v[214:217], 0
	v_mfma_f32_16x16x32_bf16 v[126:129], v[156:159], v[194:197], v[126:129]
	v_mfma_f32_16x16x32_bf16 v[122:125], v[164:167], v[194:197], v[122:125]
	v_mfma_f32_16x16x32_bf16 v[118:121], v[156:159], v[202:205], v[118:121]
	v_mfma_f32_16x16x32_bf16 v[110:113], v[164:167], v[202:205], v[110:113]
	v_mfma_f32_16x16x32_bf16 v[102:105], v[156:159], v[210:213], v[102:105]
	v_mfma_f32_16x16x32_bf16 v[94:97], v[164:167], v[210:213], v[94:97]
	v_mfma_f32_16x16x32_bf16 v[86:89], v[156:159], v[218:221], v[86:89]
	v_mfma_f32_16x16x32_bf16 v[78:81], v[164:167], v[218:221], v[78:81]
	v_mfma_f32_16x16x32_bf16 v[114:117], v[174:177], v[190:193], 0
	v_mfma_f32_16x16x32_bf16 v[106:109], v[182:185], v[190:193], 0
	v_mfma_f32_16x16x32_bf16 v[98:101], v[174:177], v[198:201], 0
	v_mfma_f32_16x16x32_bf16 v[90:93], v[182:185], v[198:201], 0
	v_mfma_f32_16x16x32_bf16 v[82:85], v[174:177], v[206:209], 0
	v_mfma_f32_16x16x32_bf16 v[74:77], v[182:185], v[206:209], 0
	v_mfma_f32_16x16x32_bf16 v[70:73], v[174:177], v[214:217], 0
	v_mfma_f32_16x16x32_bf16 v[66:69], v[182:185], v[214:217], 0
	v_mfma_f32_16x16x32_bf16 v[114:117], v[178:181], v[194:197], v[114:117]
	v_mfma_f32_16x16x32_bf16 v[106:109], v[186:189], v[194:197], v[106:109]
	v_mfma_f32_16x16x32_bf16 v[98:101], v[178:181], v[202:205], v[98:101]
	v_mfma_f32_16x16x32_bf16 v[90:93], v[186:189], v[202:205], v[90:93]
	v_mfma_f32_16x16x32_bf16 v[82:85], v[178:181], v[210:213], v[82:85]
	v_mfma_f32_16x16x32_bf16 v[74:77], v[186:189], v[210:213], v[74:77]
	v_mfma_f32_16x16x32_bf16 v[70:73], v[178:181], v[218:221], v[70:73]
	v_mfma_f32_16x16x32_bf16 v[66:69], v[186:189], v[218:221], v[66:69]
	s_barrier
	s_add_u32 s98, s26, 0x80
	s_addc_u32 s99, s27, 0
	s_add_u32 s100, s28, 0x80
	s_addc_u32 s101, s29, 0
	s_add_i32 s71, s40, s7
	s_mov_b32 m0, s71
	ds_read_b128 v[190:193], v155 offset:16384
	ds_read_b128 v[194:197], v155 offset:17408
	ds_read_b128 v[198:201], v155 offset:18432
	ds_read_b128 v[202:205], v155 offset:19456
	ds_read_b128 v[206:209], v155 offset:20480
	ds_read_b128 v[210:213], v155 offset:21504
	ds_read_b128 v[214:217], v155 offset:22528
	ds_read_b128 v[218:221], v155 offset:23552
	global_load_lds_dwordx4 v134, s[26:27]
	s_add_i32 m0, s71, 0x2000
	s_add_u32 s74, s26, 0x40000
	s_addc_u32 s75, s27, 0
	s_add_i32 s71, s41, s7
	global_load_lds_dwordx4 v130, s[26:27]
	s_mov_b32 m0, s71
	s_nop 0
	global_load_lds_dwordx4 v134, s[74:75]
	s_add_i32 m0, s71, 0x2000
	s_nop 0
	global_load_lds_dwordx4 v130, s[74:75]
	s_mov_b32 m0, s23
	s_nop 0
	global_load_lds_dwordx4 v136, s[28:29]
	s_mov_b32 m0, s31
	s_nop 0
	global_load_lds_dwordx4 v132, s[28:29]
	s_waitcnt vmcnt(8) lgkmcnt(0)
	s_barrier
	v_mfma_f32_16x16x32_bf16 v[62:65], v[146:149], v[190:193], 0
	v_mfma_f32_16x16x32_bf16 v[58:61], v[160:163], v[190:193], 0
	v_mfma_f32_16x16x32_bf16 v[54:57], v[146:149], v[198:201], 0
	v_mfma_f32_16x16x32_bf16 v[46:49], v[160:163], v[198:201], 0
	v_mfma_f32_16x16x32_bf16 v[38:41], v[146:149], v[206:209], 0
	v_mfma_f32_16x16x32_bf16 v[30:33], v[160:163], v[206:209], 0
	v_mfma_f32_16x16x32_bf16 v[22:25], v[146:149], v[214:217], 0
	v_mfma_f32_16x16x32_bf16 v[14:17], v[160:163], v[214:217], 0
	v_mfma_f32_16x16x32_bf16 v[62:65], v[156:159], v[194:197], v[62:65]
	v_mfma_f32_16x16x32_bf16 v[58:61], v[164:167], v[194:197], v[58:61]
	v_mfma_f32_16x16x32_bf16 v[54:57], v[156:159], v[202:205], v[54:57]
	v_mfma_f32_16x16x32_bf16 v[46:49], v[164:167], v[202:205], v[46:49]
	v_mfma_f32_16x16x32_bf16 v[38:41], v[156:159], v[210:213], v[38:41]
	v_mfma_f32_16x16x32_bf16 v[30:33], v[164:167], v[210:213], v[30:33]
	v_mfma_f32_16x16x32_bf16 v[22:25], v[156:159], v[218:221], v[22:25]
	v_mfma_f32_16x16x32_bf16 v[14:17], v[164:167], v[218:221], v[14:17]
	v_mfma_f32_16x16x32_bf16 v[50:53], v[174:177], v[190:193], 0
	v_mfma_f32_16x16x32_bf16 v[42:45], v[182:185], v[190:193], 0
	v_mfma_f32_16x16x32_bf16 v[34:37], v[174:177], v[198:201], 0
	v_mfma_f32_16x16x32_bf16 v[26:29], v[182:185], v[198:201], 0
	v_mfma_f32_16x16x32_bf16 v[18:21], v[174:177], v[206:209], 0
	v_mfma_f32_16x16x32_bf16 v[10:13], v[182:185], v[206:209], 0
	v_mfma_f32_16x16x32_bf16 v[6:9], v[174:177], v[214:217], 0
	v_mfma_f32_16x16x32_bf16 v[2:5], v[182:185], v[214:217], 0
	v_mfma_f32_16x16x32_bf16 v[50:53], v[178:181], v[194:197], v[50:53]
	v_mfma_f32_16x16x32_bf16 v[42:45], v[186:189], v[194:197], v[42:45]
	v_mfma_f32_16x16x32_bf16 v[34:37], v[178:181], v[202:205], v[34:37]
	v_mfma_f32_16x16x32_bf16 v[26:29], v[186:189], v[202:205], v[26:29]
	v_mfma_f32_16x16x32_bf16 v[18:21], v[178:181], v[210:213], v[18:21]
	v_mfma_f32_16x16x32_bf16 v[10:13], v[186:189], v[210:213], v[10:13]
	v_mfma_f32_16x16x32_bf16 v[6:9], v[178:181], v[218:221], v[6:9]
	v_mfma_f32_16x16x32_bf16 v[2:5], v[186:189], v[218:221], v[2:5]
	s_barrier
	s_add_i32 s71, 0, 0x18000
	v_add_u32_e32 v1, s71, v151
	s_add_i32 s74, 0, 0x1c000
	ds_read_b128 v[146:149], v1
	ds_read_b128 v[156:159], v1 offset:1024
	ds_read_b128 v[160:163], v1 offset:2048
	ds_read_b128 v[164:167], v1 offset:3072
	v_add_u32_e32 v1, s74, v151
	ds_read_b128 v[174:177], v1
	ds_read_b128 v[178:181], v1 offset:1024
	ds_read_b128 v[182:185], v1 offset:2048
	ds_read_b128 v[186:189], v1 offset:3072
	s_add_u32 s28, s28, 0x40000
	s_addc_u32 s29, s29, 0
	s_mov_b32 m0, s34
	ds_read_b128 v[190:193], v155 offset:32768
	ds_read_b128 v[194:197], v155 offset:33792
	ds_read_b128 v[198:201], v155 offset:34816
	ds_read_b128 v[202:205], v155 offset:35840
	ds_read_b128 v[206:209], v155 offset:36864
	ds_read_b128 v[210:213], v155 offset:37888
	ds_read_b128 v[214:217], v155 offset:38912
	ds_read_b128 v[218:221], v155 offset:39936
	global_load_lds_dwordx4 v136, s[28:29]
	s_mov_b32 m0, s35
	s_nop 0
	global_load_lds_dwordx4 v132, s[28:29]
	s_waitcnt vmcnt(8) lgkmcnt(0)
	s_barrier
	v_mfma_f32_16x16x32_bf16 v[126:129], v[146:149], v[190:193], v[126:129]
	v_mfma_f32_16x16x32_bf16 v[122:125], v[160:163], v[190:193], v[122:125]
	v_mfma_f32_16x16x32_bf16 v[118:121], v[146:149], v[198:201], v[118:121]
	v_mfma_f32_16x16x32_bf16 v[110:113], v[160:163], v[198:201], v[110:113]
	v_mfma_f32_16x16x32_bf16 v[102:105], v[146:149], v[206:209], v[102:105]
	v_mfma_f32_16x16x32_bf16 v[94:97], v[160:163], v[206:209], v[94:97]
	v_mfma_f32_16x16x32_bf16 v[86:89], v[146:149], v[214:217], v[86:89]
	v_mfma_f32_16x16x32_bf16 v[78:81], v[160:163], v[214:217], v[78:81]
	v_mfma_f32_16x16x32_bf16 v[126:129], v[156:159], v[194:197], v[126:129]
	v_mfma_f32_16x16x32_bf16 v[122:125], v[164:167], v[194:197], v[122:125]
	v_mfma_f32_16x16x32_bf16 v[118:121], v[156:159], v[202:205], v[118:121]
	v_mfma_f32_16x16x32_bf16 v[110:113], v[164:167], v[202:205], v[110:113]
	v_mfma_f32_16x16x32_bf16 v[102:105], v[156:159], v[210:213], v[102:105]
	v_mfma_f32_16x16x32_bf16 v[94:97], v[164:167], v[210:213], v[94:97]
	v_mfma_f32_16x16x32_bf16 v[86:89], v[156:159], v[218:221], v[86:89]
	v_mfma_f32_16x16x32_bf16 v[78:81], v[164:167], v[218:221], v[78:81]
	v_mfma_f32_16x16x32_bf16 v[114:117], v[174:177], v[190:193], v[114:117]
	v_mfma_f32_16x16x32_bf16 v[106:109], v[182:185], v[190:193], v[106:109]
	v_mfma_f32_16x16x32_bf16 v[98:101], v[174:177], v[198:201], v[98:101]
	v_mfma_f32_16x16x32_bf16 v[90:93], v[182:185], v[198:201], v[90:93]
	v_mfma_f32_16x16x32_bf16 v[82:85], v[174:177], v[206:209], v[82:85]
	v_mfma_f32_16x16x32_bf16 v[74:77], v[182:185], v[206:209], v[74:77]
	v_mfma_f32_16x16x32_bf16 v[70:73], v[174:177], v[214:217], v[70:73]
	v_mfma_f32_16x16x32_bf16 v[66:69], v[182:185], v[214:217], v[66:69]
	v_mfma_f32_16x16x32_bf16 v[114:117], v[178:181], v[194:197], v[114:117]
	v_mfma_f32_16x16x32_bf16 v[106:109], v[186:189], v[194:197], v[106:109]
	v_mfma_f32_16x16x32_bf16 v[98:101], v[178:181], v[202:205], v[98:101]
	v_mfma_f32_16x16x32_bf16 v[90:93], v[186:189], v[202:205], v[90:93]
	v_mfma_f32_16x16x32_bf16 v[82:85], v[178:181], v[210:213], v[82:85]
	v_mfma_f32_16x16x32_bf16 v[74:77], v[186:189], v[210:213], v[74:77]
	v_mfma_f32_16x16x32_bf16 v[70:73], v[178:181], v[218:221], v[70:73]
	v_mfma_f32_16x16x32_bf16 v[66:69], v[186:189], v[218:221], v[66:69]
	s_barrier
	s_add_i32 s28, s71, s7
	s_mov_b32 m0, s28
	ds_read_b128 v[190:193], v155 offset:49152
	ds_read_b128 v[194:197], v155 offset:50176
	ds_read_b128 v[198:201], v155 offset:51200
	ds_read_b128 v[202:205], v155 offset:52224
	ds_read_b128 v[206:209], v155 offset:53248
	ds_read_b128 v[210:213], v155 offset:54272
	ds_read_b128 v[214:217], v155 offset:55296
	ds_read_b128 v[218:221], v155 offset:56320
	global_load_lds_dwordx4 v134, s[98:99]
	s_add_i32 m0, s28, 0x2000
	s_add_u32 s26, s26, 0x40080
	s_addc_u32 s27, s27, 0
	s_add_i32 s28, s74, s7
	global_load_lds_dwordx4 v130, s[98:99]
	s_mov_b32 m0, s28
	s_nop 0
	global_load_lds_dwordx4 v134, s[26:27]
	s_add_i32 m0, s28, 0x2000
	s_nop 0
	global_load_lds_dwordx4 v130, s[26:27]
	s_mov_b32 m0, s37
	s_nop 0
	global_load_lds_dwordx4 v136, s[100:101]
	s_mov_b32 m0, s38
	s_nop 0
	global_load_lds_dwordx4 v132, s[100:101]
	s_waitcnt vmcnt(8) lgkmcnt(0)
	s_barrier
	v_mfma_f32_16x16x32_bf16 v[62:65], v[146:149], v[190:193], v[62:65]
	v_mfma_f32_16x16x32_bf16 v[58:61], v[160:163], v[190:193], v[58:61]
	v_mfma_f32_16x16x32_bf16 v[54:57], v[146:149], v[198:201], v[54:57]
	v_mfma_f32_16x16x32_bf16 v[46:49], v[160:163], v[198:201], v[46:49]
	v_mfma_f32_16x16x32_bf16 v[38:41], v[146:149], v[206:209], v[38:41]
	v_mfma_f32_16x16x32_bf16 v[30:33], v[160:163], v[206:209], v[30:33]
	v_mfma_f32_16x16x32_bf16 v[22:25], v[146:149], v[214:217], v[22:25]
	v_mfma_f32_16x16x32_bf16 v[14:17], v[160:163], v[214:217], v[14:17]
	v_mfma_f32_16x16x32_bf16 v[62:65], v[156:159], v[194:197], v[62:65]
	v_mfma_f32_16x16x32_bf16 v[58:61], v[164:167], v[194:197], v[58:61]
	v_mfma_f32_16x16x32_bf16 v[54:57], v[156:159], v[202:205], v[54:57]
	v_mfma_f32_16x16x32_bf16 v[46:49], v[164:167], v[202:205], v[46:49]
	v_mfma_f32_16x16x32_bf16 v[38:41], v[156:159], v[210:213], v[38:41]
	v_mfma_f32_16x16x32_bf16 v[30:33], v[164:167], v[210:213], v[30:33]
	v_mfma_f32_16x16x32_bf16 v[22:25], v[156:159], v[218:221], v[22:25]
	v_mfma_f32_16x16x32_bf16 v[14:17], v[164:167], v[218:221], v[14:17]
	v_mfma_f32_16x16x32_bf16 v[50:53], v[174:177], v[190:193], v[50:53]
	v_mfma_f32_16x16x32_bf16 v[42:45], v[182:185], v[190:193], v[42:45]
	v_mfma_f32_16x16x32_bf16 v[34:37], v[174:177], v[198:201], v[34:37]
	v_mfma_f32_16x16x32_bf16 v[26:29], v[182:185], v[198:201], v[26:29]
	v_mfma_f32_16x16x32_bf16 v[18:21], v[174:177], v[206:209], v[18:21]
	v_mfma_f32_16x16x32_bf16 v[10:13], v[182:185], v[206:209], v[10:13]
	v_mfma_f32_16x16x32_bf16 v[6:9], v[174:177], v[214:217], v[6:9]
	v_mfma_f32_16x16x32_bf16 v[2:5], v[182:185], v[214:217], v[2:5]
	v_mfma_f32_16x16x32_bf16 v[50:53], v[178:181], v[194:197], v[50:53]
	v_mfma_f32_16x16x32_bf16 v[42:45], v[186:189], v[194:197], v[42:45]
	v_mfma_f32_16x16x32_bf16 v[34:37], v[178:181], v[202:205], v[34:37]
	v_mfma_f32_16x16x32_bf16 v[26:29], v[186:189], v[202:205], v[26:29]
	v_mfma_f32_16x16x32_bf16 v[18:21], v[178:181], v[210:213], v[18:21]
	v_mfma_f32_16x16x32_bf16 v[10:13], v[186:189], v[210:213], v[10:13]
	v_mfma_f32_16x16x32_bf16 v[6:9], v[178:181], v[218:221], v[6:9]
	v_mfma_f32_16x16x32_bf16 v[2:5], v[186:189], v[218:221], v[2:5]
	s_barrier
	s_add_i32 s70, s70, 2
	s_add_u32 s24, s24, 0x100
	s_addc_u32 s25, s25, 0
	s_add_u32 s46, s46, 0x100
	s_addc_u32 s47, s47, 0
	s_cmp_gt_u32 s70, 13

.LBB0_449:
	s_ashr_i32 s21, s20, 31
	s_lshl_b64 s[22:23], s[20:21], 19
	s_add_u32 s22, s52, s22
	s_addc_u32 s23, s53, s23
	s_and_b64 s[24:25], s[4:5], exec
	s_cselect_b32 s21, s23, s31
	s_cselect_b32 s27, s22, s30
	s_ashr_i32 s19, s18, 31
	s_lshl_b64 s[24:25], s[18:19], 19
	s_add_u32 s24, s3, s24
	s_addc_u32 s25, s6, s25
	s_and_b64 s[36:37], s[4:5], exec
	s_cselect_b32 s19, s25, s35
	s_cselect_b32 s29, s24, s34
	s_add_u32 s30, s30, 0x40080
	s_addc_u32 s31, s31, 0
	s_add_u32 s55, s34, 0x100
	s_addc_u32 s70, s35, 0
	s_mov_b32 s71, -2
	s_waitcnt lgkmcnt(0)
	ds_read_b128 v[98:101], v213
	ds_read_b128 v[102:105], v213 offset:1024
	ds_read_b128 v[106:109], v213 offset:2048
	ds_read_b128 v[110:113], v213 offset:3072
	ds_read_b128 v[146:149], v214
	ds_read_b128 v[150:153], v214 offset:1024
	ds_read_b128 v[154:157], v214 offset:2048
	ds_read_b128 v[158:161], v214 offset:3072
	s_add_u32 s34, s30, 0xfffc0080
	s_addc_u32 s35, s31, -1
	s_cmp_eq_u32 s71, 12
	s_cselect_b32 s37, s21, s35
	s_cselect_b32 s36, s27, s34
	s_cselect_b32 s35, s19, s70
	s_cselect_b32 s34, s29, s55
	s_add_i32 m0, s38, 0xc000
	ds_read_b128 v[182:185], v215
	ds_read_b128 v[186:189], v215 offset:1024
	ds_read_b128 v[190:193], v215 offset:2048
	ds_read_b128 v[194:197], v215 offset:3072
	ds_read_b128 v[198:201], v215 offset:4096
	ds_read_b128 v[202:205], v215 offset:5120
	ds_read_b128 v[206:209], v215 offset:6144
	ds_read_b128 v[218:221], v215 offset:7168
	global_load_lds_dwordx4 v174, s[30:31]
	s_add_i32 m0, s38, 0xe000
	s_nop 0
	global_load_lds_dwordx4 v176, s[30:31]
	s_waitcnt vmcnt(8) lgkmcnt(0)
	s_barrier
	v_mfma_f32_16x16x32_bf16 v[142:145], v[98:101], v[182:185], 0
	v_mfma_f32_16x16x32_bf16 v[138:141], v[106:109], v[182:185], 0
	v_mfma_f32_16x16x32_bf16 v[126:129], v[98:101], v[190:193], 0
	v_mfma_f32_16x16x32_bf16 v[122:125], v[106:109], v[190:193], 0
	v_mfma_f32_16x16x32_bf16 v[94:97], v[98:101], v[198:201], 0
	v_mfma_f32_16x16x32_bf16 v[90:93], v[106:109], v[198:201], 0
	v_mfma_f32_16x16x32_bf16 v[78:81], v[98:101], v[206:209], 0
	v_mfma_f32_16x16x32_bf16 v[74:77], v[106:109], v[206:209], 0
	v_mfma_f32_16x16x32_bf16 v[142:145], v[102:105], v[186:189], v[142:145]
	v_mfma_f32_16x16x32_bf16 v[138:141], v[110:113], v[186:189], v[138:141]
	v_mfma_f32_16x16x32_bf16 v[126:129], v[102:105], v[194:197], v[126:129]
	v_mfma_f32_16x16x32_bf16 v[122:125], v[110:113], v[194:197], v[122:125]
	v_mfma_f32_16x16x32_bf16 v[94:97], v[102:105], v[202:205], v[94:97]
	v_mfma_f32_16x16x32_bf16 v[90:93], v[110:113], v[202:205], v[90:93]
	v_mfma_f32_16x16x32_bf16 v[78:81], v[102:105], v[218:221], v[78:81]
	v_mfma_f32_16x16x32_bf16 v[74:77], v[110:113], v[218:221], v[74:77]
	v_mfma_f32_16x16x32_bf16 v[134:137], v[146:149], v[182:185], 0
	v_mfma_f32_16x16x32_bf16 v[130:133], v[154:157], v[182:185], 0
	v_mfma_f32_16x16x32_bf16 v[118:121], v[146:149], v[190:193], 0
	v_mfma_f32_16x16x32_bf16 v[114:117], v[154:157], v[190:193], 0
	v_mfma_f32_16x16x32_bf16 v[86:89], v[146:149], v[198:201], 0
	v_mfma_f32_16x16x32_bf16 v[82:85], v[154:157], v[198:201], 0
	v_mfma_f32_16x16x32_bf16 v[70:73], v[146:149], v[206:209], 0
	v_mfma_f32_16x16x32_bf16 v[66:69], v[154:157], v[206:209], 0
	v_mfma_f32_16x16x32_bf16 v[134:137], v[150:153], v[186:189], v[134:137]
	v_mfma_f32_16x16x32_bf16 v[130:133], v[158:161], v[186:189], v[130:133]
	v_mfma_f32_16x16x32_bf16 v[118:121], v[150:153], v[194:197], v[118:121]
	v_mfma_f32_16x16x32_bf16 v[114:117], v[158:161], v[194:197], v[114:117]
	v_mfma_f32_16x16x32_bf16 v[86:89], v[150:153], v[202:205], v[86:89]
	v_mfma_f32_16x16x32_bf16 v[82:85], v[158:161], v[202:205], v[82:85]
	v_mfma_f32_16x16x32_bf16 v[70:73], v[150:153], v[218:221], v[70:73]
	v_mfma_f32_16x16x32_bf16 v[66:69], v[158:161], v[218:221], v[66:69]
	s_barrier
	s_add_u32 s98, s34, 0x80
	s_addc_u32 s99, s35, 0
	s_add_u32 s100, s36, 0x80
	s_addc_u32 s101, s37, 0
	s_add_i32 s74, s51, s7
	s_mov_b32 m0, s74
	ds_read_b128 v[182:185], v215 offset:16384
	ds_read_b128 v[186:189], v215 offset:17408
	ds_read_b128 v[190:193], v215 offset:18432
	ds_read_b128 v[194:197], v215 offset:19456
	ds_read_b128 v[198:201], v215 offset:20480
	ds_read_b128 v[202:205], v215 offset:21504
	ds_read_b128 v[206:209], v215 offset:22528
	ds_read_b128 v[218:221], v215 offset:23552
	s_cmp_eq_u32 s71, 12
	s_cselect_b64 exec, 0, -1
	s_cmp_lg_u32 s33, 0x100
	s_cselect_b64 exec, -1, exec
	global_load_lds_dwordx4 v164, s[34:35]
	s_add_i32 m0, s74, 0x2000
	s_add_u32 s74, s34, 0x40000
	s_addc_u32 s75, s35, 0
	s_add_i32 s76, s54, s7
	global_load_lds_dwordx4 v168, s[34:35]
	s_mov_b32 m0, s76
	s_nop 0
	global_load_lds_dwordx4 v164, s[74:75]
	s_add_i32 m0, s76, 0x2000
	s_nop 0
	global_load_lds_dwordx4 v168, s[74:75]
	s_mov_b32 m0, s38
	s_nop 0
	global_load_lds_dwordx4 v162, s[36:37]
	s_mov_b32 m0, s39
	s_nop 0
	global_load_lds_dwordx4 v166, s[36:37]
	s_mov_b64 exec, -1
	s_waitcnt vmcnt(8) lgkmcnt(0)
	s_barrier
	v_mfma_f32_16x16x32_bf16 v[62:65], v[98:101], v[182:185], 0
	v_mfma_f32_16x16x32_bf16 v[58:61], v[106:109], v[182:185], 0
	v_mfma_f32_16x16x32_bf16 v[46:49], v[98:101], v[190:193], 0
	v_mfma_f32_16x16x32_bf16 v[42:45], v[106:109], v[190:193], 0
	v_mfma_f32_16x16x32_bf16 v[30:33], v[98:101], v[198:201], 0
	v_mfma_f32_16x16x32_bf16 v[26:29], v[106:109], v[198:201], 0
	v_mfma_f32_16x16x32_bf16 v[14:17], v[98:101], v[206:209], 0
	v_mfma_f32_16x16x32_bf16 v[10:13], v[106:109], v[206:209], 0
	v_mfma_f32_16x16x32_bf16 v[62:65], v[102:105], v[186:189], v[62:65]
	v_mfma_f32_16x16x32_bf16 v[58:61], v[110:113], v[186:189], v[58:61]
	v_mfma_f32_16x16x32_bf16 v[46:49], v[102:105], v[194:197], v[46:49]
	v_mfma_f32_16x16x32_bf16 v[42:45], v[110:113], v[194:197], v[42:45]
	v_mfma_f32_16x16x32_bf16 v[30:33], v[102:105], v[202:205], v[30:33]
	v_mfma_f32_16x16x32_bf16 v[26:29], v[110:113], v[202:205], v[26:29]
	v_mfma_f32_16x16x32_bf16 v[14:17], v[102:105], v[218:221], v[14:17]
	v_mfma_f32_16x16x32_bf16 v[10:13], v[110:113], v[218:221], v[10:13]
	v_mfma_f32_16x16x32_bf16 v[54:57], v[146:149], v[182:185], 0
	v_mfma_f32_16x16x32_bf16 v[50:53], v[154:157], v[182:185], 0
	v_mfma_f32_16x16x32_bf16 v[38:41], v[146:149], v[190:193], 0
	v_mfma_f32_16x16x32_bf16 v[34:37], v[154:157], v[190:193], 0
	v_mfma_f32_16x16x32_bf16 v[22:25], v[146:149], v[198:201], 0
	v_mfma_f32_16x16x32_bf16 v[18:21], v[154:157], v[198:201], 0
	v_mfma_f32_16x16x32_bf16 v[6:9], v[146:149], v[206:209], 0
	v_mfma_f32_16x16x32_bf16 v[2:5], v[154:157], v[206:209], 0
	v_mfma_f32_16x16x32_bf16 v[54:57], v[150:153], v[186:189], v[54:57]
	v_mfma_f32_16x16x32_bf16 v[50:53], v[158:161], v[186:189], v[50:53]
	v_mfma_f32_16x16x32_bf16 v[38:41], v[150:153], v[194:197], v[38:41]
	v_mfma_f32_16x16x32_bf16 v[34:37], v[158:161], v[194:197], v[34:37]
	v_mfma_f32_16x16x32_bf16 v[22:25], v[150:153], v[202:205], v[22:25]
	v_mfma_f32_16x16x32_bf16 v[18:21], v[158:161], v[202:205], v[18:21]
	v_mfma_f32_16x16x32_bf16 v[6:9], v[150:153], v[218:221], v[6:9]
	v_mfma_f32_16x16x32_bf16 v[2:5], v[158:161], v[218:221], v[2:5]
	s_barrier
	s_add_i32 s74, 0, 0x18000
	v_add_u32_e32 v1, s74, v173
	s_add_i32 s75, 0, 0x1c000
	ds_read_b128 v[98:101], v1
	ds_read_b128 v[102:105], v1 offset:1024
	ds_read_b128 v[106:109], v1 offset:2048
	ds_read_b128 v[110:113], v1 offset:3072
	v_add_u32_e32 v1, s75, v173
	ds_read_b128 v[146:149], v1
	ds_read_b128 v[150:153], v1 offset:1024
	ds_read_b128 v[154:157], v1 offset:2048
	ds_read_b128 v[158:161], v1 offset:3072
	s_add_u32 s36, s36, 0x40000
	s_addc_u32 s37, s37, 0
	s_mov_b32 m0, s40
	ds_read_b128 v[182:185], v215 offset:32768
	ds_read_b128 v[186:189], v215 offset:33792
	ds_read_b128 v[190:193], v215 offset:34816
	ds_read_b128 v[194:197], v215 offset:35840
	ds_read_b128 v[198:201], v215 offset:36864
	ds_read_b128 v[202:205], v215 offset:37888
	ds_read_b128 v[206:209], v215 offset:38912
	ds_read_b128 v[218:221], v215 offset:39936
	s_cmp_eq_u32 s71, 12
	s_cselect_b64 exec, 0, -1
	s_cmp_lg_u32 s33, 0x100
	s_cselect_b64 exec, -1, exec
	global_load_lds_dwordx4 v162, s[36:37]
	s_mov_b32 m0, s41
	s_nop 0
	global_load_lds_dwordx4 v166, s[36:37]
	s_mov_b64 exec, -1
	s_waitcnt vmcnt(8) lgkmcnt(0)
	s_barrier
	v_mfma_f32_16x16x32_bf16 v[142:145], v[98:101], v[182:185], v[142:145]
	v_mfma_f32_16x16x32_bf16 v[138:141], v[106:109], v[182:185], v[138:141]
	v_mfma_f32_16x16x32_bf16 v[126:129], v[98:101], v[190:193], v[126:129]
	v_mfma_f32_16x16x32_bf16 v[122:125], v[106:109], v[190:193], v[122:125]
	v_mfma_f32_16x16x32_bf16 v[94:97], v[98:101], v[198:201], v[94:97]
	v_mfma_f32_16x16x32_bf16 v[90:93], v[106:109], v[198:201], v[90:93]
	v_mfma_f32_16x16x32_bf16 v[78:81], v[98:101], v[206:209], v[78:81]
	v_mfma_f32_16x16x32_bf16 v[74:77], v[106:109], v[206:209], v[74:77]
	v_mfma_f32_16x16x32_bf16 v[142:145], v[102:105], v[186:189], v[142:145]
	v_mfma_f32_16x16x32_bf16 v[138:141], v[110:113], v[186:189], v[138:141]
	v_mfma_f32_16x16x32_bf16 v[126:129], v[102:105], v[194:197], v[126:129]
	v_mfma_f32_16x16x32_bf16 v[122:125], v[110:113], v[194:197], v[122:125]
	v_mfma_f32_16x16x32_bf16 v[94:97], v[102:105], v[202:205], v[94:97]
	v_mfma_f32_16x16x32_bf16 v[90:93], v[110:113], v[202:205], v[90:93]
	v_mfma_f32_16x16x32_bf16 v[78:81], v[102:105], v[218:221], v[78:81]
	v_mfma_f32_16x16x32_bf16 v[74:77], v[110:113], v[218:221], v[74:77]
	v_mfma_f32_16x16x32_bf16 v[134:137], v[146:149], v[182:185], v[134:137]
	v_mfma_f32_16x16x32_bf16 v[130:133], v[154:157], v[182:185], v[130:133]
	v_mfma_f32_16x16x32_bf16 v[118:121], v[146:149], v[190:193], v[118:121]
	v_mfma_f32_16x16x32_bf16 v[114:117], v[154:157], v[190:193], v[114:117]
	v_mfma_f32_16x16x32_bf16 v[86:89], v[146:149], v[198:201], v[86:89]
	v_mfma_f32_16x16x32_bf16 v[82:85], v[154:157], v[198:201], v[82:85]
	v_mfma_f32_16x16x32_bf16 v[70:73], v[146:149], v[206:209], v[70:73]
	v_mfma_f32_16x16x32_bf16 v[66:69], v[154:157], v[206:209], v[66:69]
	v_mfma_f32_16x16x32_bf16 v[134:137], v[150:153], v[186:189], v[134:137]
	v_mfma_f32_16x16x32_bf16 v[130:133], v[158:161], v[186:189], v[130:133]
	v_mfma_f32_16x16x32_bf16 v[118:121], v[150:153], v[194:197], v[118:121]
	v_mfma_f32_16x16x32_bf16 v[114:117], v[158:161], v[194:197], v[114:117]
	v_mfma_f32_16x16x32_bf16 v[86:89], v[150:153], v[202:205], v[86:89]
	v_mfma_f32_16x16x32_bf16 v[82:85], v[158:161], v[202:205], v[82:85]
	v_mfma_f32_16x16x32_bf16 v[70:73], v[150:153], v[218:221], v[70:73]
	v_mfma_f32_16x16x32_bf16 v[66:69], v[158:161], v[218:221], v[66:69]
	s_barrier
	s_add_i32 s36, s74, s7
	s_mov_b32 m0, s36
	ds_read_b128 v[182:185], v215 offset:49152
	ds_read_b128 v[186:189], v215 offset:50176
	ds_read_b128 v[190:193], v215 offset:51200
	ds_read_b128 v[194:197], v215 offset:52224
	ds_read_b128 v[198:201], v215 offset:53248
	ds_read_b128 v[202:205], v215 offset:54272
	ds_read_b128 v[206:209], v215 offset:55296
	ds_read_b128 v[218:221], v215 offset:56320
	s_cmp_eq_u32 s71, 12
	s_cselect_b64 exec, 0, -1
	s_cmp_lg_u32 s33, 0x100
	s_cselect_b64 exec, -1, exec
	global_load_lds_dwordx4 v164, s[98:99]
	s_add_i32 m0, s36, 0x2000
	s_add_u32 s34, s34, 0x40080
	s_addc_u32 s35, s35, 0
	s_add_i32 s36, s75, s7
	global_load_lds_dwordx4 v168, s[98:99]
	s_mov_b32 m0, s36
	s_nop 0
	global_load_lds_dwordx4 v164, s[34:35]
	s_add_i32 m0, s36, 0x2000
	s_nop 0
	global_load_lds_dwordx4 v168, s[34:35]
	s_mov_b32 m0, s47
	s_nop 0
	global_load_lds_dwordx4 v162, s[100:101]
	s_mov_b32 m0, s48
	s_nop 0
	global_load_lds_dwordx4 v166, s[100:101]
	s_mov_b64 exec, -1
	s_waitcnt vmcnt(8) lgkmcnt(0)
	s_barrier
	v_mfma_f32_16x16x32_bf16 v[62:65], v[98:101], v[182:185], v[62:65]
	v_mfma_f32_16x16x32_bf16 v[58:61], v[106:109], v[182:185], v[58:61]
	v_mfma_f32_16x16x32_bf16 v[46:49], v[98:101], v[190:193], v[46:49]
	v_mfma_f32_16x16x32_bf16 v[42:45], v[106:109], v[190:193], v[42:45]
	v_mfma_f32_16x16x32_bf16 v[30:33], v[98:101], v[198:201], v[30:33]
	v_mfma_f32_16x16x32_bf16 v[26:29], v[106:109], v[198:201], v[26:29]
	v_mfma_f32_16x16x32_bf16 v[14:17], v[98:101], v[206:209], v[14:17]
	v_mfma_f32_16x16x32_bf16 v[10:13], v[106:109], v[206:209], v[10:13]
	v_mfma_f32_16x16x32_bf16 v[62:65], v[102:105], v[186:189], v[62:65]
	v_mfma_f32_16x16x32_bf16 v[58:61], v[110:113], v[186:189], v[58:61]
	v_mfma_f32_16x16x32_bf16 v[46:49], v[102:105], v[194:197], v[46:49]
	v_mfma_f32_16x16x32_bf16 v[42:45], v[110:113], v[194:197], v[42:45]
	v_mfma_f32_16x16x32_bf16 v[30:33], v[102:105], v[202:205], v[30:33]
	v_mfma_f32_16x16x32_bf16 v[26:29], v[110:113], v[202:205], v[26:29]
	v_mfma_f32_16x16x32_bf16 v[14:17], v[102:105], v[218:221], v[14:17]
	v_mfma_f32_16x16x32_bf16 v[10:13], v[110:113], v[218:221], v[10:13]
	v_mfma_f32_16x16x32_bf16 v[54:57], v[146:149], v[182:185], v[54:57]
	v_mfma_f32_16x16x32_bf16 v[50:53], v[154:157], v[182:185], v[50:53]
	v_mfma_f32_16x16x32_bf16 v[38:41], v[146:149], v[190:193], v[38:41]
	v_mfma_f32_16x16x32_bf16 v[34:37], v[154:157], v[190:193], v[34:37]
	v_mfma_f32_16x16x32_bf16 v[22:25], v[146:149], v[198:201], v[22:25]
	v_mfma_f32_16x16x32_bf16 v[18:21], v[154:157], v[198:201], v[18:21]
	v_mfma_f32_16x16x32_bf16 v[6:9], v[146:149], v[206:209], v[6:9]
	v_mfma_f32_16x16x32_bf16 v[2:5], v[154:157], v[206:209], v[2:5]
	v_mfma_f32_16x16x32_bf16 v[54:57], v[150:153], v[186:189], v[54:57]
	v_mfma_f32_16x16x32_bf16 v[50:53], v[158:161], v[186:189], v[50:53]
	v_mfma_f32_16x16x32_bf16 v[38:41], v[150:153], v[194:197], v[38:41]
	v_mfma_f32_16x16x32_bf16 v[34:37], v[158:161], v[194:197], v[34:37]
	v_mfma_f32_16x16x32_bf16 v[22:25], v[150:153], v[202:205], v[22:25]
	v_mfma_f32_16x16x32_bf16 v[18:21], v[158:161], v[202:205], v[18:21]
	v_mfma_f32_16x16x32_bf16 v[6:9], v[150:153], v[218:221], v[6:9]
	v_mfma_f32_16x16x32_bf16 v[2:5], v[158:161], v[218:221], v[2:5]
	s_barrier
	s_add_i32 s71, s71, 2
	s_add_u32 s30, s30, 0x100
	s_addc_u32 s31, s31, 0
	s_add_u32 s55, s55, 0x100
	s_addc_u32 s70, s70, 0
	s_cmp_gt_u32 s71, 13

.LBB0_556:
	s_ashr_i32 s41, s40, 31
	s_lshl_b64 s[42:43], s[40:41], 19
	s_add_u32 s42, s68, s42
	s_addc_u32 s43, s69, s43
	s_and_b64 s[44:45], s[4:5], exec
	s_cselect_b32 s41, s43, s9
	s_cselect_b32 s47, s42, s8
	s_ashr_i32 s39, s38, 31
	s_lshl_b64 s[44:45], s[38:39], 19
	s_add_u32 s44, s54, s44
	s_addc_u32 s45, s55, s45
	s_and_b64 s[50:51], s[4:5], exec
	s_cselect_b32 s39, s45, s49
	s_cselect_b32 vcc_lo, s44, s48
	s_add_u32 s8, s8, 0x40080
	s_addc_u32 s9, s9, 0
	s_add_u32 vcc_hi, s48, 0x100
	s_addc_u32 s3, s49, 0
	s_mov_b32 s7, -2
	s_waitcnt lgkmcnt(0)
	ds_read_b128 v[30:33], v219
	ds_read_b128 v[54:57], v219 offset:1024
	ds_read_b128 v[118:121], v219 offset:2048
	ds_read_b128 v[122:125], v219 offset:3072
	ds_read_b128 v[146:149], v220
	ds_read_b128 v[150:153], v220 offset:1024
	ds_read_b128 v[154:157], v220 offset:2048
	ds_read_b128 v[158:161], v220 offset:3072
	s_add_u32 s48, s8, 0xfffc0080
	s_addc_u32 s49, s9, -1
	s_cmp_eq_u32 s7, 12
	s_cselect_b32 s51, s41, s49
	s_cselect_b32 s50, s47, s48
	s_cselect_b32 s49, s39, s3
	s_cselect_b32 s48, vcc_lo, vcc_hi
	s_add_i32 m0, s70, 0xc000
	ds_read_b128 v[162:165], v221
	ds_read_b128 v[166:169], v221 offset:1024
	ds_read_b128 v[194:197], v221 offset:2048
	ds_read_b128 v[198:201], v221 offset:3072
	ds_read_b128 v[202:205], v221 offset:4096
	ds_read_b128 v[206:209], v221 offset:5120
	ds_read_b128 v[224:227], v221 offset:6144
	ds_read_b128 v[228:231], v221 offset:7168
	global_load_lds_dwordx4 v186, s[8:9]
	s_add_i32 m0, s70, 0xe000
	s_nop 0
	global_load_lds_dwordx4 v188, s[8:9]
	s_waitcnt vmcnt(8) lgkmcnt(0)
	s_barrier
	v_mfma_f32_16x16x32_bf16 v[62:65], v[30:33], v[162:165], 0
	v_mfma_f32_16x16x32_bf16 v[42:45], v[118:121], v[162:165], 0
	v_mfma_f32_16x16x32_bf16 v[50:53], v[30:33], v[194:197], 0
	v_mfma_f32_16x16x32_bf16 v[38:41], v[118:121], v[194:197], 0
	v_mfma_f32_16x16x32_bf16 v[46:49], v[30:33], v[202:205], 0
	v_mfma_f32_16x16x32_bf16 v[34:37], v[118:121], v[202:205], 0
	v_mfma_f32_16x16x32_bf16 v[142:145], v[30:33], v[224:227], 0
	v_mfma_f32_16x16x32_bf16 v[82:85], v[118:121], v[224:227], 0
	v_mfma_f32_16x16x32_bf16 v[62:65], v[54:57], v[166:169], v[62:65]
	v_mfma_f32_16x16x32_bf16 v[42:45], v[122:125], v[166:169], v[42:45]
	v_mfma_f32_16x16x32_bf16 v[50:53], v[54:57], v[198:201], v[50:53]
	v_mfma_f32_16x16x32_bf16 v[38:41], v[122:125], v[198:201], v[38:41]
	v_mfma_f32_16x16x32_bf16 v[46:49], v[54:57], v[206:209], v[46:49]
	v_mfma_f32_16x16x32_bf16 v[34:37], v[122:125], v[206:209], v[34:37]
	v_mfma_f32_16x16x32_bf16 v[142:145], v[54:57], v[228:231], v[142:145]
	v_mfma_f32_16x16x32_bf16 v[82:85], v[122:125], v[228:231], v[82:85]
	v_mfma_f32_16x16x32_bf16 v[134:137], v[146:149], v[162:165], 0
	v_mfma_f32_16x16x32_bf16 v[74:77], v[154:157], v[162:165], 0
	v_mfma_f32_16x16x32_bf16 v[130:133], v[146:149], v[194:197], 0
	v_mfma_f32_16x16x32_bf16 v[70:73], v[154:157], v[194:197], 0
	v_mfma_f32_16x16x32_bf16 v[78:81], v[146:149], v[202:205], 0
	v_mfma_f32_16x16x32_bf16 v[66:69], v[154:157], v[202:205], 0
	v_mfma_f32_16x16x32_bf16 v[138:141], v[146:149], v[224:227], 0
	v_mfma_f32_16x16x32_bf16 v[98:101], v[154:157], v[224:227], 0
	v_mfma_f32_16x16x32_bf16 v[134:137], v[150:153], v[166:169], v[134:137]
	v_mfma_f32_16x16x32_bf16 v[74:77], v[158:161], v[166:169], v[74:77]
	v_mfma_f32_16x16x32_bf16 v[130:133], v[150:153], v[198:201], v[130:133]
	v_mfma_f32_16x16x32_bf16 v[70:73], v[158:161], v[198:201], v[70:73]
	v_mfma_f32_16x16x32_bf16 v[78:81], v[150:153], v[206:209], v[78:81]
	v_mfma_f32_16x16x32_bf16 v[66:69], v[158:161], v[206:209], v[66:69]
	v_mfma_f32_16x16x32_bf16 v[138:141], v[150:153], v[228:231], v[138:141]
	v_mfma_f32_16x16x32_bf16 v[98:101], v[158:161], v[228:231], v[98:101]
	s_barrier
	s_add_u32 s98, s48, 0x80
	s_addc_u32 s99, s49, 0
	s_add_u32 s100, s50, 0x80
	s_addc_u32 s101, s51, 0
	s_add_i32 s84, s93, s64
	s_mov_b32 m0, s84
	ds_read_b128 v[162:165], v221 offset:16384
	ds_read_b128 v[166:169], v221 offset:17408
	ds_read_b128 v[194:197], v221 offset:18432
	ds_read_b128 v[198:201], v221 offset:19456
	ds_read_b128 v[202:205], v221 offset:20480
	ds_read_b128 v[206:209], v221 offset:21504
	ds_read_b128 v[224:227], v221 offset:22528
	ds_read_b128 v[228:231], v221 offset:23552
	global_load_lds_dwordx4 v176, s[48:49]
	s_add_i32 m0, s84, 0x2000
	s_add_u32 s84, s48, 0x40000
	s_addc_u32 s85, s49, 0
	s_add_i32 s86, s90, s64
	global_load_lds_dwordx4 v180, s[48:49]
	s_mov_b32 m0, s86
	s_nop 0
	global_load_lds_dwordx4 v176, s[84:85]
	s_add_i32 m0, s86, 0x2000
	s_nop 0
	global_load_lds_dwordx4 v180, s[84:85]
	s_mov_b32 m0, s70
	s_nop 0
	global_load_lds_dwordx4 v174, s[50:51]
	s_mov_b32 m0, s71
	s_nop 0
	global_load_lds_dwordx4 v178, s[50:51]
	s_waitcnt vmcnt(8) lgkmcnt(0)
	s_barrier
	v_mfma_f32_16x16x32_bf16 v[94:97], v[30:33], v[162:165], 0
	v_mfma_f32_16x16x32_bf16 v[10:13], v[118:121], v[162:165], 0
	v_mfma_f32_16x16x32_bf16 v[90:93], v[30:33], v[194:197], 0
	v_mfma_f32_16x16x32_bf16 v[6:9], v[118:121], v[194:197], 0
	v_mfma_f32_16x16x32_bf16 v[86:89], v[30:33], v[202:205], 0
	v_mfma_f32_16x16x32_bf16 v[2:5], v[118:121], v[202:205], 0
	v_mfma_f32_16x16x32_bf16 v[26:29], v[118:121], v[224:227], 0
	v_mfma_f32_16x16x32_bf16 v[94:97], v[54:57], v[166:169], v[94:97]
	v_mfma_f32_16x16x32_bf16 v[10:13], v[122:125], v[166:169], v[10:13]
	v_mfma_f32_16x16x32_bf16 v[90:93], v[54:57], v[198:201], v[90:93]
	v_mfma_f32_16x16x32_bf16 v[6:9], v[122:125], v[198:201], v[6:9]
	v_mfma_f32_16x16x32_bf16 v[86:89], v[54:57], v[206:209], v[86:89]
	v_mfma_f32_16x16x32_bf16 v[2:5], v[122:125], v[206:209], v[2:5]
	v_mfma_f32_16x16x32_bf16 v[30:33], v[30:33], v[224:227], 0
	v_mfma_f32_16x16x32_bf16 v[26:29], v[122:125], v[228:231], v[26:29]
	v_mfma_f32_16x16x32_bf16 v[30:33], v[54:57], v[228:231], v[30:33]
	v_mfma_f32_16x16x32_bf16 v[22:25], v[154:157], v[162:165], 0
	v_mfma_f32_16x16x32_bf16 v[106:109], v[146:149], v[194:197], 0
	v_mfma_f32_16x16x32_bf16 v[18:21], v[154:157], v[194:197], 0
	v_mfma_f32_16x16x32_bf16 v[102:105], v[146:149], v[202:205], 0
	v_mfma_f32_16x16x32_bf16 v[14:17], v[154:157], v[202:205], 0
	v_mfma_f32_16x16x32_bf16 v[58:61], v[154:157], v[224:227], 0
	v_mfma_f32_16x16x32_bf16 v[54:57], v[146:149], v[162:165], 0
	v_mfma_f32_16x16x32_bf16 v[22:25], v[158:161], v[166:169], v[22:25]
	v_mfma_f32_16x16x32_bf16 v[106:109], v[150:153], v[198:201], v[106:109]
	v_mfma_f32_16x16x32_bf16 v[18:21], v[158:161], v[198:201], v[18:21]
	v_mfma_f32_16x16x32_bf16 v[102:105], v[150:153], v[206:209], v[102:105]
	v_mfma_f32_16x16x32_bf16 v[14:17], v[158:161], v[206:209], v[14:17]
	v_mfma_f32_16x16x32_bf16 v[110:113], v[146:149], v[224:227], 0
	v_mfma_f32_16x16x32_bf16 v[58:61], v[158:161], v[228:231], v[58:61]
	v_mfma_f32_16x16x32_bf16 v[54:57], v[150:153], v[166:169], v[54:57]
	v_mfma_f32_16x16x32_bf16 v[118:121], v[150:153], v[228:231], v[110:113]
	s_barrier
	s_add_i32 s84, 0, 0x18000
	v_add_u32_e32 v1, s84, v210
	s_add_i32 s85, 0, 0x1c000
	ds_read_b128 v[110:113], v1
	ds_read_b128 v[114:117], v1 offset:1024
	ds_read_b128 v[122:125], v1 offset:2048
	ds_read_b128 v[126:129], v1 offset:3072
	v_add_u32_e32 v1, s85, v210
	ds_read_b128 v[146:149], v1
	ds_read_b128 v[150:153], v1 offset:1024
	ds_read_b128 v[154:157], v1 offset:2048
	ds_read_b128 v[158:161], v1 offset:3072
	s_add_u32 s50, s50, 0x40000
	s_addc_u32 s51, s51, 0
	s_mov_b32 m0, s74
	ds_read_b128 v[162:165], v221 offset:32768
	ds_read_b128 v[166:169], v221 offset:33792
	ds_read_b128 v[194:197], v221 offset:34816
	ds_read_b128 v[198:201], v221 offset:35840
	ds_read_b128 v[202:205], v221 offset:36864
	ds_read_b128 v[206:209], v221 offset:37888
	ds_read_b128 v[224:227], v221 offset:38912
	ds_read_b128 v[228:231], v221 offset:39936
	global_load_lds_dwordx4 v174, s[50:51]
	s_mov_b32 m0, s75
	s_nop 0
	global_load_lds_dwordx4 v178, s[50:51]
	s_waitcnt vmcnt(8) lgkmcnt(0)
	s_barrier
	v_mfma_f32_16x16x32_bf16 v[62:65], v[110:113], v[162:165], v[62:65]
	v_mfma_f32_16x16x32_bf16 v[42:45], v[122:125], v[162:165], v[42:45]
	v_mfma_f32_16x16x32_bf16 v[50:53], v[110:113], v[194:197], v[50:53]
	v_mfma_f32_16x16x32_bf16 v[38:41], v[122:125], v[194:197], v[38:41]
	v_mfma_f32_16x16x32_bf16 v[46:49], v[110:113], v[202:205], v[46:49]
	v_mfma_f32_16x16x32_bf16 v[34:37], v[122:125], v[202:205], v[34:37]
	v_mfma_f32_16x16x32_bf16 v[142:145], v[110:113], v[224:227], v[142:145]
	v_mfma_f32_16x16x32_bf16 v[82:85], v[122:125], v[224:227], v[82:85]
	v_mfma_f32_16x16x32_bf16 v[62:65], v[114:117], v[166:169], v[62:65]
	v_mfma_f32_16x16x32_bf16 v[42:45], v[126:129], v[166:169], v[42:45]
	v_mfma_f32_16x16x32_bf16 v[50:53], v[114:117], v[198:201], v[50:53]
	v_mfma_f32_16x16x32_bf16 v[38:41], v[126:129], v[198:201], v[38:41]
	v_mfma_f32_16x16x32_bf16 v[46:49], v[114:117], v[206:209], v[46:49]
	v_mfma_f32_16x16x32_bf16 v[34:37], v[126:129], v[206:209], v[34:37]
	v_mfma_f32_16x16x32_bf16 v[142:145], v[114:117], v[228:231], v[142:145]
	v_mfma_f32_16x16x32_bf16 v[82:85], v[126:129], v[228:231], v[82:85]
	v_mfma_f32_16x16x32_bf16 v[134:137], v[146:149], v[162:165], v[134:137]
	v_mfma_f32_16x16x32_bf16 v[74:77], v[154:157], v[162:165], v[74:77]
	v_mfma_f32_16x16x32_bf16 v[130:133], v[146:149], v[194:197], v[130:133]
	v_mfma_f32_16x16x32_bf16 v[70:73], v[154:157], v[194:197], v[70:73]
	v_mfma_f32_16x16x32_bf16 v[78:81], v[146:149], v[202:205], v[78:81]
	v_mfma_f32_16x16x32_bf16 v[66:69], v[154:157], v[202:205], v[66:69]
	v_mfma_f32_16x16x32_bf16 v[138:141], v[146:149], v[224:227], v[138:141]
	v_mfma_f32_16x16x32_bf16 v[98:101], v[154:157], v[224:227], v[98:101]
	v_mfma_f32_16x16x32_bf16 v[134:137], v[150:153], v[166:169], v[134:137]
	v_mfma_f32_16x16x32_bf16 v[74:77], v[158:161], v[166:169], v[74:77]
	v_mfma_f32_16x16x32_bf16 v[130:133], v[150:153], v[198:201], v[130:133]
	v_mfma_f32_16x16x32_bf16 v[70:73], v[158:161], v[198:201], v[70:73]
	v_mfma_f32_16x16x32_bf16 v[78:81], v[150:153], v[206:209], v[78:81]
	v_mfma_f32_16x16x32_bf16 v[66:69], v[158:161], v[206:209], v[66:69]
	v_mfma_f32_16x16x32_bf16 v[138:141], v[150:153], v[228:231], v[138:141]
	v_mfma_f32_16x16x32_bf16 v[98:101], v[158:161], v[228:231], v[98:101]
	s_barrier
	s_add_i32 s50, s84, s64
	s_mov_b32 m0, s50
	ds_read_b128 v[162:165], v221 offset:49152
	ds_read_b128 v[166:169], v221 offset:50176
	ds_read_b128 v[194:197], v221 offset:51200
	ds_read_b128 v[198:201], v221 offset:52224
	ds_read_b128 v[202:205], v221 offset:53248
	ds_read_b128 v[206:209], v221 offset:54272
	ds_read_b128 v[224:227], v221 offset:55296
	ds_read_b128 v[228:231], v221 offset:56320
	global_load_lds_dwordx4 v176, s[98:99]
	s_add_i32 m0, s50, 0x2000
	s_add_u32 s48, s48, 0x40080
	s_addc_u32 s49, s49, 0
	s_add_i32 s50, s85, s64
	global_load_lds_dwordx4 v180, s[98:99]
	s_mov_b32 m0, s50
	s_nop 0
	global_load_lds_dwordx4 v176, s[48:49]
	s_add_i32 m0, s50, 0x2000
	s_nop 0
	global_load_lds_dwordx4 v180, s[48:49]
	s_mov_b32 m0, s77
	s_nop 0
	global_load_lds_dwordx4 v174, s[100:101]
	s_mov_b32 m0, s78
	s_nop 0
	global_load_lds_dwordx4 v178, s[100:101]
	s_waitcnt vmcnt(8) lgkmcnt(0)
	s_barrier
	v_mfma_f32_16x16x32_bf16 v[94:97], v[110:113], v[162:165], v[94:97]
	v_mfma_f32_16x16x32_bf16 v[10:13], v[122:125], v[162:165], v[10:13]
	v_mfma_f32_16x16x32_bf16 v[90:93], v[110:113], v[194:197], v[90:93]
	v_mfma_f32_16x16x32_bf16 v[6:9], v[122:125], v[194:197], v[6:9]
	v_mfma_f32_16x16x32_bf16 v[86:89], v[110:113], v[202:205], v[86:89]
	v_mfma_f32_16x16x32_bf16 v[2:5], v[122:125], v[202:205], v[2:5]
	v_mfma_f32_16x16x32_bf16 v[30:33], v[110:113], v[224:227], v[30:33]
	v_mfma_f32_16x16x32_bf16 v[26:29], v[122:125], v[224:227], v[26:29]
	v_mfma_f32_16x16x32_bf16 v[94:97], v[114:117], v[166:169], v[94:97]
	v_mfma_f32_16x16x32_bf16 v[10:13], v[126:129], v[166:169], v[10:13]
	v_mfma_f32_16x16x32_bf16 v[90:93], v[114:117], v[198:201], v[90:93]
	v_mfma_f32_16x16x32_bf16 v[6:9], v[126:129], v[198:201], v[6:9]
	v_mfma_f32_16x16x32_bf16 v[86:89], v[114:117], v[206:209], v[86:89]
	v_mfma_f32_16x16x32_bf16 v[2:5], v[126:129], v[206:209], v[2:5]
	v_mfma_f32_16x16x32_bf16 v[114:117], v[114:117], v[228:231], v[30:33]
	v_mfma_f32_16x16x32_bf16 v[26:29], v[126:129], v[228:231], v[26:29]
	v_mfma_f32_16x16x32_bf16 v[30:33], v[146:149], v[162:165], v[54:57]
	v_mfma_f32_16x16x32_bf16 v[110:113], v[150:153], v[166:169], v[30:33]
	v_mfma_f32_16x16x32_bf16 v[30:33], v[146:149], v[194:197], v[106:109]
	v_mfma_f32_16x16x32_bf16 v[106:109], v[150:153], v[198:201], v[30:33]
	v_mfma_f32_16x16x32_bf16 v[30:33], v[146:149], v[202:205], v[102:105]
	v_mfma_f32_16x16x32_bf16 v[102:105], v[150:153], v[206:209], v[30:33]
	v_mfma_f32_16x16x32_bf16 v[30:33], v[146:149], v[224:227], v[118:121]
	v_mfma_f32_16x16x32_bf16 v[22:25], v[154:157], v[162:165], v[22:25]
	v_mfma_f32_16x16x32_bf16 v[18:21], v[154:157], v[194:197], v[18:21]
	v_mfma_f32_16x16x32_bf16 v[14:17], v[154:157], v[202:205], v[14:17]
	v_mfma_f32_16x16x32_bf16 v[126:129], v[150:153], v[228:231], v[30:33]
	v_mfma_f32_16x16x32_bf16 v[30:33], v[154:157], v[224:227], v[58:61]
	v_mfma_f32_16x16x32_bf16 v[22:25], v[158:161], v[166:169], v[22:25]
	v_mfma_f32_16x16x32_bf16 v[18:21], v[158:161], v[198:201], v[18:21]
	v_mfma_f32_16x16x32_bf16 v[14:17], v[158:161], v[206:209], v[14:17]
	v_mfma_f32_16x16x32_bf16 v[58:61], v[158:161], v[228:231], v[30:33]
	s_barrier
	s_add_i32 s7, s7, 2
	s_add_u32 s8, s8, 0x100
	s_addc_u32 s9, s9, 0
	s_add_u32 vcc_hi, vcc_hi, 0x100
	s_addc_u32 s3, s3, 0
	s_cmp_gt_u32 s7, 13

.LBB0_732:
	s_add_u32 s24, s24, 0xb0080
	s_addc_u32 s25, s25, 0
	s_add_u32 s49, s26, 0x100
	s_addc_u32 s50, s27, 0
	s_mov_b32 s51, -2
	s_waitcnt lgkmcnt(0)
	ds_read_b128 v[78:81], v184
	ds_read_b128 v[86:89], v184 offset:1024
	ds_read_b128 v[90:93], v184 offset:2048
	ds_read_b128 v[94:97], v184 offset:3072
	ds_read_b128 v[146:149], v185
	ds_read_b128 v[150:153], v185 offset:1024
	ds_read_b128 v[176:179], v185 offset:2048
	ds_read_b128 v[180:183], v185 offset:3072
	s_add_u32 s26, s24, 0xfff50080
	s_addc_u32 s27, s25, -1
	s_cmp_eq_u32 s51, 40
	s_cselect_b32 s29, s9, s27
	s_cselect_b32 s28, s8, s26
	s_cselect_b32 s27, s23, s50
	s_cselect_b32 s26, s22, s49
	s_add_i32 m0, s34, 0xc000
	ds_read_b128 v[188:191], v186
	ds_read_b128 v[192:195], v186 offset:1024
	ds_read_b128 v[196:199], v186 offset:2048
	ds_read_b128 v[200:203], v186 offset:3072
	ds_read_b128 v[204:207], v186 offset:4096
	ds_read_b128 v[208:211], v186 offset:5120
	ds_read_b128 v[212:215], v186 offset:6144
	ds_read_b128 v[216:219], v186 offset:7168
	global_load_lds_dwordx4 v162, s[24:25]
	s_add_i32 m0, s34, 0xe000
	s_nop 0
	global_load_lds_dwordx4 v164, s[24:25]
	s_waitcnt vmcnt(8) lgkmcnt(0)
	s_barrier
	v_mfma_f32_16x16x32_bf16 v[142:145], v[78:81], v[188:191], 0
	v_mfma_f32_16x16x32_bf16 v[138:141], v[90:93], v[188:191], 0
	v_mfma_f32_16x16x32_bf16 v[126:129], v[78:81], v[196:199], 0
	v_mfma_f32_16x16x32_bf16 v[122:125], v[90:93], v[196:199], 0
	v_mfma_f32_16x16x32_bf16 v[110:113], v[78:81], v[204:207], 0
	v_mfma_f32_16x16x32_bf16 v[106:109], v[90:93], v[204:207], 0
	v_mfma_f32_16x16x32_bf16 v[82:85], v[78:81], v[212:215], 0
	v_mfma_f32_16x16x32_bf16 v[74:77], v[90:93], v[212:215], 0
	v_mfma_f32_16x16x32_bf16 v[142:145], v[86:89], v[192:195], v[142:145]
	v_mfma_f32_16x16x32_bf16 v[138:141], v[94:97], v[192:195], v[138:141]
	v_mfma_f32_16x16x32_bf16 v[126:129], v[86:89], v[200:203], v[126:129]
	v_mfma_f32_16x16x32_bf16 v[122:125], v[94:97], v[200:203], v[122:125]
	v_mfma_f32_16x16x32_bf16 v[110:113], v[86:89], v[208:211], v[110:113]
	v_mfma_f32_16x16x32_bf16 v[106:109], v[94:97], v[208:211], v[106:109]
	v_mfma_f32_16x16x32_bf16 v[82:85], v[86:89], v[216:219], v[82:85]
	v_mfma_f32_16x16x32_bf16 v[74:77], v[94:97], v[216:219], v[74:77]
	v_mfma_f32_16x16x32_bf16 v[134:137], v[146:149], v[188:191], 0
	v_mfma_f32_16x16x32_bf16 v[130:133], v[176:179], v[188:191], 0
	v_mfma_f32_16x16x32_bf16 v[118:121], v[146:149], v[196:199], 0
	v_mfma_f32_16x16x32_bf16 v[114:117], v[176:179], v[196:199], 0
	v_mfma_f32_16x16x32_bf16 v[102:105], v[146:149], v[204:207], 0
	v_mfma_f32_16x16x32_bf16 v[98:101], v[176:179], v[204:207], 0
	v_mfma_f32_16x16x32_bf16 v[70:73], v[146:149], v[212:215], 0
	v_mfma_f32_16x16x32_bf16 v[66:69], v[176:179], v[212:215], 0
	v_mfma_f32_16x16x32_bf16 v[134:137], v[150:153], v[192:195], v[134:137]
	v_mfma_f32_16x16x32_bf16 v[130:133], v[180:183], v[192:195], v[130:133]
	v_mfma_f32_16x16x32_bf16 v[118:121], v[150:153], v[200:203], v[118:121]
	v_mfma_f32_16x16x32_bf16 v[114:117], v[180:183], v[200:203], v[114:117]
	v_mfma_f32_16x16x32_bf16 v[102:105], v[150:153], v[208:211], v[102:105]
	v_mfma_f32_16x16x32_bf16 v[98:101], v[180:183], v[208:211], v[98:101]
	v_mfma_f32_16x16x32_bf16 v[70:73], v[150:153], v[216:219], v[70:73]
	v_mfma_f32_16x16x32_bf16 v[66:69], v[180:183], v[216:219], v[66:69]
	s_barrier
	s_add_u32 s98, s26, 0x80
	s_addc_u32 s99, s27, 0
	s_add_u32 s100, s28, 0x80
	s_addc_u32 s101, s29, 0
	s_add_i32 s54, s43, s31
	s_mov_b32 m0, s54
	ds_read_b128 v[188:191], v186 offset:16384
	ds_read_b128 v[192:195], v186 offset:17408
	ds_read_b128 v[196:199], v186 offset:18432
	ds_read_b128 v[200:203], v186 offset:19456
	ds_read_b128 v[204:207], v186 offset:20480
	ds_read_b128 v[208:211], v186 offset:21504
	ds_read_b128 v[212:215], v186 offset:22528
	ds_read_b128 v[216:219], v186 offset:23552
	s_cmp_eq_u32 s51, 40
	s_cselect_b64 exec, 0, -1
	s_cmp_lg_u32 s33, 0x100
	s_cselect_b64 exec, -1, exec
	global_load_lds_dwordx4 v156, s[26:27]
	s_add_i32 m0, s54, 0x2000
	s_add_u32 s54, s26, 0xb0000
	s_addc_u32 s55, s27, 0
	s_add_i32 s58, s44, s31
	global_load_lds_dwordx4 v160, s[26:27]
	s_mov_b32 m0, s58
	s_nop 0
	global_load_lds_dwordx4 v156, s[54:55]
	s_add_i32 m0, s58, 0x2000
	s_nop 0
	global_load_lds_dwordx4 v160, s[54:55]
	s_mov_b32 m0, s34
	s_nop 0
	global_load_lds_dwordx4 v154, s[28:29]
	s_mov_b32 m0, s35
	s_nop 0
	global_load_lds_dwordx4 v158, s[28:29]
	s_mov_b64 exec, -1
	s_waitcnt vmcnt(8) lgkmcnt(0)
	s_barrier
	v_mfma_f32_16x16x32_bf16 v[62:65], v[78:81], v[188:191], 0
	v_mfma_f32_16x16x32_bf16 v[58:61], v[90:93], v[188:191], 0
	v_mfma_f32_16x16x32_bf16 v[46:49], v[78:81], v[196:199], 0
	v_mfma_f32_16x16x32_bf16 v[42:45], v[90:93], v[196:199], 0
	v_mfma_f32_16x16x32_bf16 v[30:33], v[78:81], v[204:207], 0
	v_mfma_f32_16x16x32_bf16 v[26:29], v[90:93], v[204:207], 0
	v_mfma_f32_16x16x32_bf16 v[14:17], v[78:81], v[212:215], 0
	v_mfma_f32_16x16x32_bf16 v[10:13], v[90:93], v[212:215], 0
	v_mfma_f32_16x16x32_bf16 v[62:65], v[86:89], v[192:195], v[62:65]
	v_mfma_f32_16x16x32_bf16 v[58:61], v[94:97], v[192:195], v[58:61]
	v_mfma_f32_16x16x32_bf16 v[46:49], v[86:89], v[200:203], v[46:49]
	v_mfma_f32_16x16x32_bf16 v[42:45], v[94:97], v[200:203], v[42:45]
	v_mfma_f32_16x16x32_bf16 v[30:33], v[86:89], v[208:211], v[30:33]
	v_mfma_f32_16x16x32_bf16 v[26:29], v[94:97], v[208:211], v[26:29]
	v_mfma_f32_16x16x32_bf16 v[14:17], v[86:89], v[216:219], v[14:17]
	v_mfma_f32_16x16x32_bf16 v[10:13], v[94:97], v[216:219], v[10:13]
	v_mfma_f32_16x16x32_bf16 v[54:57], v[146:149], v[188:191], 0
	v_mfma_f32_16x16x32_bf16 v[50:53], v[176:179], v[188:191], 0
	v_mfma_f32_16x16x32_bf16 v[38:41], v[146:149], v[196:199], 0
	v_mfma_f32_16x16x32_bf16 v[34:37], v[176:179], v[196:199], 0
	v_mfma_f32_16x16x32_bf16 v[22:25], v[146:149], v[204:207], 0
	v_mfma_f32_16x16x32_bf16 v[18:21], v[176:179], v[204:207], 0
	v_mfma_f32_16x16x32_bf16 v[6:9], v[146:149], v[212:215], 0
	v_mfma_f32_16x16x32_bf16 v[2:5], v[176:179], v[212:215], 0
	v_mfma_f32_16x16x32_bf16 v[54:57], v[150:153], v[192:195], v[54:57]
	v_mfma_f32_16x16x32_bf16 v[50:53], v[180:183], v[192:195], v[50:53]
	v_mfma_f32_16x16x32_bf16 v[38:41], v[150:153], v[200:203], v[38:41]
	v_mfma_f32_16x16x32_bf16 v[34:37], v[180:183], v[200:203], v[34:37]
	v_mfma_f32_16x16x32_bf16 v[22:25], v[150:153], v[208:211], v[22:25]
	v_mfma_f32_16x16x32_bf16 v[18:21], v[180:183], v[208:211], v[18:21]
	v_mfma_f32_16x16x32_bf16 v[6:9], v[150:153], v[216:219], v[6:9]
	v_mfma_f32_16x16x32_bf16 v[2:5], v[180:183], v[216:219], v[2:5]
	s_barrier
	s_add_i32 s54, 0, 0x18000
	v_add_u32_e32 v1, s54, v173
	s_add_i32 s55, 0, 0x1c000
	ds_read_b128 v[78:81], v1
	ds_read_b128 v[86:89], v1 offset:1024
	ds_read_b128 v[90:93], v1 offset:2048
	ds_read_b128 v[94:97], v1 offset:3072
	v_add_u32_e32 v1, s55, v173
	ds_read_b128 v[146:149], v1
	ds_read_b128 v[150:153], v1 offset:1024
	ds_read_b128 v[176:179], v1 offset:2048
	ds_read_b128 v[180:183], v1 offset:3072
	s_add_u32 s28, s28, 0xb0000
	s_addc_u32 s29, s29, 0
	s_mov_b32 m0, s36
	ds_read_b128 v[188:191], v186 offset:32768
	ds_read_b128 v[192:195], v186 offset:33792
	ds_read_b128 v[196:199], v186 offset:34816
	ds_read_b128 v[200:203], v186 offset:35840
	ds_read_b128 v[204:207], v186 offset:36864
	ds_read_b128 v[208:211], v186 offset:37888
	ds_read_b128 v[212:215], v186 offset:38912
	ds_read_b128 v[216:219], v186 offset:39936
	s_cmp_eq_u32 s51, 40
	s_cselect_b64 exec, 0, -1
	s_cmp_lg_u32 s33, 0x100
	s_cselect_b64 exec, -1, exec
	global_load_lds_dwordx4 v154, s[28:29]
	s_mov_b32 m0, s37
	s_nop 0
	global_load_lds_dwordx4 v158, s[28:29]
	s_mov_b64 exec, -1
	s_waitcnt vmcnt(8) lgkmcnt(0)
	s_barrier
	v_mfma_f32_16x16x32_bf16 v[142:145], v[78:81], v[188:191], v[142:145]
	v_mfma_f32_16x16x32_bf16 v[138:141], v[90:93], v[188:191], v[138:141]
	v_mfma_f32_16x16x32_bf16 v[126:129], v[78:81], v[196:199], v[126:129]
	v_mfma_f32_16x16x32_bf16 v[122:125], v[90:93], v[196:199], v[122:125]
	v_mfma_f32_16x16x32_bf16 v[110:113], v[78:81], v[204:207], v[110:113]
	v_mfma_f32_16x16x32_bf16 v[106:109], v[90:93], v[204:207], v[106:109]
	v_mfma_f32_16x16x32_bf16 v[82:85], v[78:81], v[212:215], v[82:85]
	v_mfma_f32_16x16x32_bf16 v[74:77], v[90:93], v[212:215], v[74:77]
	v_mfma_f32_16x16x32_bf16 v[142:145], v[86:89], v[192:195], v[142:145]
	v_mfma_f32_16x16x32_bf16 v[138:141], v[94:97], v[192:195], v[138:141]
	v_mfma_f32_16x16x32_bf16 v[126:129], v[86:89], v[200:203], v[126:129]
	v_mfma_f32_16x16x32_bf16 v[122:125], v[94:97], v[200:203], v[122:125]
	v_mfma_f32_16x16x32_bf16 v[110:113], v[86:89], v[208:211], v[110:113]
	v_mfma_f32_16x16x32_bf16 v[106:109], v[94:97], v[208:211], v[106:109]
	v_mfma_f32_16x16x32_bf16 v[82:85], v[86:89], v[216:219], v[82:85]
	v_mfma_f32_16x16x32_bf16 v[74:77], v[94:97], v[216:219], v[74:77]
	v_mfma_f32_16x16x32_bf16 v[134:137], v[146:149], v[188:191], v[134:137]
	v_mfma_f32_16x16x32_bf16 v[130:133], v[176:179], v[188:191], v[130:133]
	v_mfma_f32_16x16x32_bf16 v[118:121], v[146:149], v[196:199], v[118:121]
	v_mfma_f32_16x16x32_bf16 v[114:117], v[176:179], v[196:199], v[114:117]
	v_mfma_f32_16x16x32_bf16 v[102:105], v[146:149], v[204:207], v[102:105]
	v_mfma_f32_16x16x32_bf16 v[98:101], v[176:179], v[204:207], v[98:101]
	v_mfma_f32_16x16x32_bf16 v[70:73], v[146:149], v[212:215], v[70:73]
	v_mfma_f32_16x16x32_bf16 v[66:69], v[176:179], v[212:215], v[66:69]
	v_mfma_f32_16x16x32_bf16 v[134:137], v[150:153], v[192:195], v[134:137]
	v_mfma_f32_16x16x32_bf16 v[130:133], v[180:183], v[192:195], v[130:133]
	v_mfma_f32_16x16x32_bf16 v[118:121], v[150:153], v[200:203], v[118:121]
	v_mfma_f32_16x16x32_bf16 v[114:117], v[180:183], v[200:203], v[114:117]
	v_mfma_f32_16x16x32_bf16 v[102:105], v[150:153], v[208:211], v[102:105]
	v_mfma_f32_16x16x32_bf16 v[98:101], v[180:183], v[208:211], v[98:101]
	v_mfma_f32_16x16x32_bf16 v[70:73], v[150:153], v[216:219], v[70:73]
	v_mfma_f32_16x16x32_bf16 v[66:69], v[180:183], v[216:219], v[66:69]
	s_barrier
	s_add_i32 s28, s54, s31
	s_mov_b32 m0, s28
	ds_read_b128 v[188:191], v186 offset:49152
	ds_read_b128 v[192:195], v186 offset:50176
	ds_read_b128 v[196:199], v186 offset:51200
	ds_read_b128 v[200:203], v186 offset:52224
	ds_read_b128 v[204:207], v186 offset:53248
	ds_read_b128 v[208:211], v186 offset:54272
	ds_read_b128 v[212:215], v186 offset:55296
	ds_read_b128 v[216:219], v186 offset:56320
	s_cmp_eq_u32 s51, 40
	s_cselect_b64 exec, 0, -1
	s_cmp_lg_u32 s33, 0x100
	s_cselect_b64 exec, -1, exec
	global_load_lds_dwordx4 v156, s[98:99]
	s_add_i32 m0, s28, 0x2000
	s_add_u32 s26, s26, 0xb0080
	s_addc_u32 s27, s27, 0
	s_add_i32 s28, s55, s31
	global_load_lds_dwordx4 v160, s[98:99]
	s_mov_b32 m0, s28
	s_nop 0
	global_load_lds_dwordx4 v156, s[26:27]
	s_add_i32 m0, s28, 0x2000
	s_nop 0
	global_load_lds_dwordx4 v160, s[26:27]
	s_mov_b32 m0, s41
	s_nop 0
	global_load_lds_dwordx4 v154, s[100:101]
	s_mov_b32 m0, s42
	s_nop 0
	global_load_lds_dwordx4 v158, s[100:101]
	s_mov_b64 exec, -1
	s_waitcnt vmcnt(8) lgkmcnt(0)
	s_barrier
	v_mfma_f32_16x16x32_bf16 v[62:65], v[78:81], v[188:191], v[62:65]
	v_mfma_f32_16x16x32_bf16 v[58:61], v[90:93], v[188:191], v[58:61]
	v_mfma_f32_16x16x32_bf16 v[46:49], v[78:81], v[196:199], v[46:49]
	v_mfma_f32_16x16x32_bf16 v[42:45], v[90:93], v[196:199], v[42:45]
	v_mfma_f32_16x16x32_bf16 v[30:33], v[78:81], v[204:207], v[30:33]
	v_mfma_f32_16x16x32_bf16 v[26:29], v[90:93], v[204:207], v[26:29]
	v_mfma_f32_16x16x32_bf16 v[14:17], v[78:81], v[212:215], v[14:17]
	v_mfma_f32_16x16x32_bf16 v[10:13], v[90:93], v[212:215], v[10:13]
	v_mfma_f32_16x16x32_bf16 v[62:65], v[86:89], v[192:195], v[62:65]
	v_mfma_f32_16x16x32_bf16 v[58:61], v[94:97], v[192:195], v[58:61]
	v_mfma_f32_16x16x32_bf16 v[46:49], v[86:89], v[200:203], v[46:49]
	v_mfma_f32_16x16x32_bf16 v[42:45], v[94:97], v[200:203], v[42:45]
	v_mfma_f32_16x16x32_bf16 v[30:33], v[86:89], v[208:211], v[30:33]
	v_mfma_f32_16x16x32_bf16 v[26:29], v[94:97], v[208:211], v[26:29]
	v_mfma_f32_16x16x32_bf16 v[14:17], v[86:89], v[216:219], v[14:17]
	v_mfma_f32_16x16x32_bf16 v[10:13], v[94:97], v[216:219], v[10:13]
	v_mfma_f32_16x16x32_bf16 v[54:57], v[146:149], v[188:191], v[54:57]
	v_mfma_f32_16x16x32_bf16 v[50:53], v[176:179], v[188:191], v[50:53]
	v_mfma_f32_16x16x32_bf16 v[38:41], v[146:149], v[196:199], v[38:41]
	v_mfma_f32_16x16x32_bf16 v[34:37], v[176:179], v[196:199], v[34:37]
	v_mfma_f32_16x16x32_bf16 v[22:25], v[146:149], v[204:207], v[22:25]
	v_mfma_f32_16x16x32_bf16 v[18:21], v[176:179], v[204:207], v[18:21]
	v_mfma_f32_16x16x32_bf16 v[6:9], v[146:149], v[212:215], v[6:9]
	v_mfma_f32_16x16x32_bf16 v[2:5], v[176:179], v[212:215], v[2:5]
	v_mfma_f32_16x16x32_bf16 v[54:57], v[150:153], v[192:195], v[54:57]
	v_mfma_f32_16x16x32_bf16 v[50:53], v[180:183], v[192:195], v[50:53]
	v_mfma_f32_16x16x32_bf16 v[38:41], v[150:153], v[200:203], v[38:41]
	v_mfma_f32_16x16x32_bf16 v[34:37], v[180:183], v[200:203], v[34:37]
	v_mfma_f32_16x16x32_bf16 v[22:25], v[150:153], v[208:211], v[22:25]
	v_mfma_f32_16x16x32_bf16 v[18:21], v[180:183], v[208:211], v[18:21]
	v_mfma_f32_16x16x32_bf16 v[6:9], v[150:153], v[216:219], v[6:9]
	v_mfma_f32_16x16x32_bf16 v[2:5], v[180:183], v[216:219], v[2:5]
	s_barrier
	s_add_i32 s51, s51, 2
	s_add_u32 s24, s24, 0x100
	s_addc_u32 s25, s25, 0
	s_add_u32 s49, s49, 0x100
	s_addc_u32 s50, s50, 0
	s_cmp_gt_u32 s51, 41

.LBB0_1316:
	s_ashr_i32 s45, s44, 31
	s_lshl_b64 s[46:47], s[44:45], 19
	s_add_u32 s46, s68, s46
	s_addc_u32 s47, s69, s47
	s_and_b64 s[48:49], s[4:5], exec
	s_cselect_b32 s45, s47, s9
	s_cselect_b32 s51, s46, s8
	s_ashr_i32 s43, s42, 31
	s_lshl_b64 s[48:49], s[42:43], 19
	s_add_u32 s48, s7, s48
	s_addc_u32 s49, s56, s49
	s_and_b64 s[54:55], s[4:5], exec
	s_cselect_b32 s43, s49, s53
	s_cselect_b32 s90, s48, s52
	s_add_u32 s8, s8, 0x40080
	s_addc_u32 s9, s9, 0
	s_add_u32 s91, s52, 0x100
	s_addc_u32 s92, s53, 0
	s_mov_b32 s93, -2
	ds_read_b128 v[30:33], v219
	ds_read_b128 v[54:57], v219 offset:1024
	ds_read_b128 v[118:121], v219 offset:2048
	ds_read_b128 v[122:125], v219 offset:3072
	ds_read_b128 v[146:149], v220
	ds_read_b128 v[150:153], v220 offset:1024
	ds_read_b128 v[154:157], v220 offset:2048
	ds_read_b128 v[158:161], v220 offset:3072
	s_add_u32 s52, s8, 0xfffc0080
	s_addc_u32 s53, s9, -1
	s_cmp_eq_u32 s93, 12
	s_cselect_b32 s55, s45, s53
	s_cselect_b32 s54, s51, s52
	s_cselect_b32 s53, s43, s92
	s_cselect_b32 s52, s90, s91
	s_add_i32 m0, s59, 0xc000
	ds_read_b128 v[162:165], v221
	ds_read_b128 v[166:169], v221 offset:1024
	ds_read_b128 v[196:199], v221 offset:2048
	ds_read_b128 v[200:203], v221 offset:3072
	ds_read_b128 v[204:207], v221 offset:4096
	ds_read_b128 v[208:211], v221 offset:5120
	ds_read_b128 v[224:227], v221 offset:6144
	ds_read_b128 v[228:231], v221 offset:7168
	global_load_lds_dwordx4 v188, s[8:9]
	s_add_i32 m0, s59, 0xe000
	s_nop 0
	global_load_lds_dwordx4 v190, s[8:9]
	s_waitcnt vmcnt(8) lgkmcnt(0)
	s_barrier
	v_mfma_f32_16x16x32_bf16 v[62:65], v[30:33], v[162:165], 0
	v_mfma_f32_16x16x32_bf16 v[42:45], v[118:121], v[162:165], 0
	v_mfma_f32_16x16x32_bf16 v[50:53], v[30:33], v[196:199], 0
	v_mfma_f32_16x16x32_bf16 v[38:41], v[118:121], v[196:199], 0
	v_mfma_f32_16x16x32_bf16 v[46:49], v[30:33], v[204:207], 0
	v_mfma_f32_16x16x32_bf16 v[34:37], v[118:121], v[204:207], 0
	v_mfma_f32_16x16x32_bf16 v[142:145], v[30:33], v[224:227], 0
	v_mfma_f32_16x16x32_bf16 v[82:85], v[118:121], v[224:227], 0
	v_mfma_f32_16x16x32_bf16 v[62:65], v[54:57], v[166:169], v[62:65]
	v_mfma_f32_16x16x32_bf16 v[42:45], v[122:125], v[166:169], v[42:45]
	v_mfma_f32_16x16x32_bf16 v[50:53], v[54:57], v[200:203], v[50:53]
	v_mfma_f32_16x16x32_bf16 v[38:41], v[122:125], v[200:203], v[38:41]
	v_mfma_f32_16x16x32_bf16 v[46:49], v[54:57], v[208:211], v[46:49]
	v_mfma_f32_16x16x32_bf16 v[34:37], v[122:125], v[208:211], v[34:37]
	v_mfma_f32_16x16x32_bf16 v[142:145], v[54:57], v[228:231], v[142:145]
	v_mfma_f32_16x16x32_bf16 v[82:85], v[122:125], v[228:231], v[82:85]
	v_mfma_f32_16x16x32_bf16 v[134:137], v[146:149], v[162:165], 0
	v_mfma_f32_16x16x32_bf16 v[74:77], v[154:157], v[162:165], 0
	v_mfma_f32_16x16x32_bf16 v[130:133], v[146:149], v[196:199], 0
	v_mfma_f32_16x16x32_bf16 v[70:73], v[154:157], v[196:199], 0
	v_mfma_f32_16x16x32_bf16 v[78:81], v[146:149], v[204:207], 0
	v_mfma_f32_16x16x32_bf16 v[66:69], v[154:157], v[204:207], 0
	v_mfma_f32_16x16x32_bf16 v[138:141], v[146:149], v[224:227], 0
	v_mfma_f32_16x16x32_bf16 v[98:101], v[154:157], v[224:227], 0
	v_mfma_f32_16x16x32_bf16 v[134:137], v[150:153], v[166:169], v[134:137]
	v_mfma_f32_16x16x32_bf16 v[74:77], v[158:161], v[166:169], v[74:77]
	v_mfma_f32_16x16x32_bf16 v[130:133], v[150:153], v[200:203], v[130:133]
	v_mfma_f32_16x16x32_bf16 v[70:73], v[158:161], v[200:203], v[70:73]
	v_mfma_f32_16x16x32_bf16 v[78:81], v[150:153], v[208:211], v[78:81]
	v_mfma_f32_16x16x32_bf16 v[66:69], v[158:161], v[208:211], v[66:69]
	v_mfma_f32_16x16x32_bf16 v[138:141], v[150:153], v[228:231], v[138:141]
	v_mfma_f32_16x16x32_bf16 v[98:101], v[158:161], v[228:231], v[98:101]
	s_barrier
	s_add_u32 s98, s52, 0x80
	s_addc_u32 s99, s53, 0
	s_add_u32 s100, s54, 0x80
	s_addc_u32 s101, s55, 0
	s_add_i32 s84, s75, s57
	s_mov_b32 m0, s84
	ds_read_b128 v[162:165], v221 offset:16384
	ds_read_b128 v[166:169], v221 offset:17408
	ds_read_b128 v[196:199], v221 offset:18432
	ds_read_b128 v[200:203], v221 offset:19456
	ds_read_b128 v[204:207], v221 offset:20480
	ds_read_b128 v[208:211], v221 offset:21504
	ds_read_b128 v[224:227], v221 offset:22528
	ds_read_b128 v[228:231], v221 offset:23552
	global_load_lds_dwordx4 v178, s[52:53]
	s_add_i32 m0, s84, 0x2000
	s_add_u32 s84, s52, 0x40000
	s_addc_u32 s85, s53, 0
	s_add_i32 s86, s76, s57
	global_load_lds_dwordx4 v182, s[52:53]
	s_mov_b32 m0, s86
	s_nop 0
	global_load_lds_dwordx4 v178, s[84:85]
	s_add_i32 m0, s86, 0x2000
	s_nop 0
	global_load_lds_dwordx4 v182, s[84:85]
	s_mov_b32 m0, s59
	s_nop 0
	global_load_lds_dwordx4 v176, s[54:55]
	s_mov_b32 m0, s62
	s_nop 0
	global_load_lds_dwordx4 v180, s[54:55]
	s_waitcnt vmcnt(8) lgkmcnt(0)
	s_barrier
	v_mfma_f32_16x16x32_bf16 v[94:97], v[30:33], v[162:165], 0
	v_mfma_f32_16x16x32_bf16 v[10:13], v[118:121], v[162:165], 0
	v_mfma_f32_16x16x32_bf16 v[90:93], v[30:33], v[196:199], 0
	v_mfma_f32_16x16x32_bf16 v[6:9], v[118:121], v[196:199], 0
	v_mfma_f32_16x16x32_bf16 v[86:89], v[30:33], v[204:207], 0
	v_mfma_f32_16x16x32_bf16 v[2:5], v[118:121], v[204:207], 0
	v_mfma_f32_16x16x32_bf16 v[26:29], v[118:121], v[224:227], 0
	v_mfma_f32_16x16x32_bf16 v[94:97], v[54:57], v[166:169], v[94:97]
	v_mfma_f32_16x16x32_bf16 v[10:13], v[122:125], v[166:169], v[10:13]
	v_mfma_f32_16x16x32_bf16 v[90:93], v[54:57], v[200:203], v[90:93]
	v_mfma_f32_16x16x32_bf16 v[6:9], v[122:125], v[200:203], v[6:9]
	v_mfma_f32_16x16x32_bf16 v[86:89], v[54:57], v[208:211], v[86:89]
	v_mfma_f32_16x16x32_bf16 v[2:5], v[122:125], v[208:211], v[2:5]
	v_mfma_f32_16x16x32_bf16 v[30:33], v[30:33], v[224:227], 0
	v_mfma_f32_16x16x32_bf16 v[26:29], v[122:125], v[228:231], v[26:29]
	v_mfma_f32_16x16x32_bf16 v[30:33], v[54:57], v[228:231], v[30:33]
	v_mfma_f32_16x16x32_bf16 v[22:25], v[154:157], v[162:165], 0
	v_mfma_f32_16x16x32_bf16 v[106:109], v[146:149], v[196:199], 0
	v_mfma_f32_16x16x32_bf16 v[18:21], v[154:157], v[196:199], 0
	v_mfma_f32_16x16x32_bf16 v[102:105], v[146:149], v[204:207], 0
	v_mfma_f32_16x16x32_bf16 v[14:17], v[154:157], v[204:207], 0
	v_mfma_f32_16x16x32_bf16 v[58:61], v[154:157], v[224:227], 0
	v_mfma_f32_16x16x32_bf16 v[54:57], v[146:149], v[162:165], 0
	v_mfma_f32_16x16x32_bf16 v[22:25], v[158:161], v[166:169], v[22:25]
	v_mfma_f32_16x16x32_bf16 v[106:109], v[150:153], v[200:203], v[106:109]
	v_mfma_f32_16x16x32_bf16 v[18:21], v[158:161], v[200:203], v[18:21]
	v_mfma_f32_16x16x32_bf16 v[102:105], v[150:153], v[208:211], v[102:105]
	v_mfma_f32_16x16x32_bf16 v[14:17], v[158:161], v[208:211], v[14:17]
	v_mfma_f32_16x16x32_bf16 v[110:113], v[146:149], v[224:227], 0
	v_mfma_f32_16x16x32_bf16 v[58:61], v[158:161], v[228:231], v[58:61]
	v_mfma_f32_16x16x32_bf16 v[54:57], v[150:153], v[166:169], v[54:57]
	v_mfma_f32_16x16x32_bf16 v[118:121], v[150:153], v[228:231], v[110:113]
	s_barrier
	s_add_i32 s84, 0, 0x18000
	s_add_i32 s85, 0, 0x1c000
	v_add_u32_e32 v126, s84, v175
	v_add_u32_e32 v158, s85, v175
	ds_read_b128 v[110:113], v126
	ds_read_b128 v[114:117], v126 offset:1024
	ds_read_b128 v[122:125], v126 offset:2048
	ds_read_b128 v[126:129], v126 offset:3072
	ds_read_b128 v[146:149], v158
	ds_read_b128 v[150:153], v158 offset:1024
	ds_read_b128 v[154:157], v158 offset:2048
	ds_read_b128 v[158:161], v158 offset:3072
	s_add_u32 s54, s54, 0x40000
	s_addc_u32 s55, s55, 0
	s_mov_b32 m0, s63
	ds_read_b128 v[162:165], v221 offset:32768
	ds_read_b128 v[166:169], v221 offset:33792
	ds_read_b128 v[196:199], v221 offset:34816
	ds_read_b128 v[200:203], v221 offset:35840
	ds_read_b128 v[204:207], v221 offset:36864
	ds_read_b128 v[208:211], v221 offset:37888
	ds_read_b128 v[224:227], v221 offset:38912
	ds_read_b128 v[228:231], v221 offset:39936
	global_load_lds_dwordx4 v176, s[54:55]
	s_mov_b32 m0, s64
	s_nop 0
	global_load_lds_dwordx4 v180, s[54:55]
	s_waitcnt vmcnt(8) lgkmcnt(0)
	s_barrier
	v_mfma_f32_16x16x32_bf16 v[62:65], v[110:113], v[162:165], v[62:65]
	v_mfma_f32_16x16x32_bf16 v[42:45], v[122:125], v[162:165], v[42:45]
	v_mfma_f32_16x16x32_bf16 v[50:53], v[110:113], v[196:199], v[50:53]
	v_mfma_f32_16x16x32_bf16 v[38:41], v[122:125], v[196:199], v[38:41]
	v_mfma_f32_16x16x32_bf16 v[46:49], v[110:113], v[204:207], v[46:49]
	v_mfma_f32_16x16x32_bf16 v[34:37], v[122:125], v[204:207], v[34:37]
	v_mfma_f32_16x16x32_bf16 v[142:145], v[110:113], v[224:227], v[142:145]
	v_mfma_f32_16x16x32_bf16 v[82:85], v[122:125], v[224:227], v[82:85]
	v_mfma_f32_16x16x32_bf16 v[62:65], v[114:117], v[166:169], v[62:65]
	v_mfma_f32_16x16x32_bf16 v[42:45], v[126:129], v[166:169], v[42:45]
	v_mfma_f32_16x16x32_bf16 v[50:53], v[114:117], v[200:203], v[50:53]
	v_mfma_f32_16x16x32_bf16 v[38:41], v[126:129], v[200:203], v[38:41]
	v_mfma_f32_16x16x32_bf16 v[46:49], v[114:117], v[208:211], v[46:49]
	v_mfma_f32_16x16x32_bf16 v[34:37], v[126:129], v[208:211], v[34:37]
	v_mfma_f32_16x16x32_bf16 v[142:145], v[114:117], v[228:231], v[142:145]
	v_mfma_f32_16x16x32_bf16 v[82:85], v[126:129], v[228:231], v[82:85]
	v_mfma_f32_16x16x32_bf16 v[134:137], v[146:149], v[162:165], v[134:137]
	v_mfma_f32_16x16x32_bf16 v[74:77], v[154:157], v[162:165], v[74:77]
	v_mfma_f32_16x16x32_bf16 v[130:133], v[146:149], v[196:199], v[130:133]
	v_mfma_f32_16x16x32_bf16 v[70:73], v[154:157], v[196:199], v[70:73]
	v_mfma_f32_16x16x32_bf16 v[78:81], v[146:149], v[204:207], v[78:81]
	v_mfma_f32_16x16x32_bf16 v[66:69], v[154:157], v[204:207], v[66:69]
	v_mfma_f32_16x16x32_bf16 v[138:141], v[146:149], v[224:227], v[138:141]
	v_mfma_f32_16x16x32_bf16 v[98:101], v[154:157], v[224:227], v[98:101]
	v_mfma_f32_16x16x32_bf16 v[134:137], v[150:153], v[166:169], v[134:137]
	v_mfma_f32_16x16x32_bf16 v[74:77], v[158:161], v[166:169], v[74:77]
	v_mfma_f32_16x16x32_bf16 v[130:133], v[150:153], v[200:203], v[130:133]
	v_mfma_f32_16x16x32_bf16 v[70:73], v[158:161], v[200:203], v[70:73]
	v_mfma_f32_16x16x32_bf16 v[78:81], v[150:153], v[208:211], v[78:81]
	v_mfma_f32_16x16x32_bf16 v[66:69], v[158:161], v[208:211], v[66:69]
	v_mfma_f32_16x16x32_bf16 v[138:141], v[150:153], v[228:231], v[138:141]
	v_mfma_f32_16x16x32_bf16 v[98:101], v[158:161], v[228:231], v[98:101]
	s_barrier
	s_add_i32 s54, s84, s57
	s_mov_b32 m0, s54
	ds_read_b128 v[162:165], v221 offset:49152
	ds_read_b128 v[166:169], v221 offset:50176
	ds_read_b128 v[196:199], v221 offset:51200
	ds_read_b128 v[200:203], v221 offset:52224
	ds_read_b128 v[204:207], v221 offset:53248
	ds_read_b128 v[208:211], v221 offset:54272
	ds_read_b128 v[224:227], v221 offset:55296
	ds_read_b128 v[228:231], v221 offset:56320
	global_load_lds_dwordx4 v178, s[98:99]
	s_add_i32 m0, s54, 0x2000
	s_add_u32 s52, s52, 0x40080
	s_addc_u32 s53, s53, 0
	s_add_i32 s54, s85, s57
	global_load_lds_dwordx4 v182, s[98:99]
	s_mov_b32 m0, s54
	s_nop 0
	global_load_lds_dwordx4 v178, s[52:53]
	s_add_i32 m0, s54, 0x2000
	s_nop 0
	global_load_lds_dwordx4 v182, s[52:53]
	s_mov_b32 m0, s70
	s_nop 0
	global_load_lds_dwordx4 v176, s[100:101]
	s_mov_b32 m0, s71
	s_nop 0
	global_load_lds_dwordx4 v180, s[100:101]
	s_waitcnt vmcnt(8) lgkmcnt(0)
	s_barrier
	v_mfma_f32_16x16x32_bf16 v[94:97], v[110:113], v[162:165], v[94:97]
	v_mfma_f32_16x16x32_bf16 v[10:13], v[122:125], v[162:165], v[10:13]
	v_mfma_f32_16x16x32_bf16 v[90:93], v[110:113], v[196:199], v[90:93]
	v_mfma_f32_16x16x32_bf16 v[6:9], v[122:125], v[196:199], v[6:9]
	v_mfma_f32_16x16x32_bf16 v[86:89], v[110:113], v[204:207], v[86:89]
	v_mfma_f32_16x16x32_bf16 v[2:5], v[122:125], v[204:207], v[2:5]
	v_mfma_f32_16x16x32_bf16 v[30:33], v[110:113], v[224:227], v[30:33]
	v_mfma_f32_16x16x32_bf16 v[26:29], v[122:125], v[224:227], v[26:29]
	v_mfma_f32_16x16x32_bf16 v[94:97], v[114:117], v[166:169], v[94:97]
	v_mfma_f32_16x16x32_bf16 v[10:13], v[126:129], v[166:169], v[10:13]
	v_mfma_f32_16x16x32_bf16 v[90:93], v[114:117], v[200:203], v[90:93]
	v_mfma_f32_16x16x32_bf16 v[6:9], v[126:129], v[200:203], v[6:9]
	v_mfma_f32_16x16x32_bf16 v[86:89], v[114:117], v[208:211], v[86:89]
	v_mfma_f32_16x16x32_bf16 v[2:5], v[126:129], v[208:211], v[2:5]
	v_mfma_f32_16x16x32_bf16 v[114:117], v[114:117], v[228:231], v[30:33]
	v_mfma_f32_16x16x32_bf16 v[26:29], v[126:129], v[228:231], v[26:29]
	v_mfma_f32_16x16x32_bf16 v[30:33], v[146:149], v[162:165], v[54:57]
	v_mfma_f32_16x16x32_bf16 v[110:113], v[150:153], v[166:169], v[30:33]
	v_mfma_f32_16x16x32_bf16 v[30:33], v[146:149], v[196:199], v[106:109]
	v_mfma_f32_16x16x32_bf16 v[106:109], v[150:153], v[200:203], v[30:33]
	v_mfma_f32_16x16x32_bf16 v[30:33], v[146:149], v[204:207], v[102:105]
	v_mfma_f32_16x16x32_bf16 v[102:105], v[150:153], v[208:211], v[30:33]
	v_mfma_f32_16x16x32_bf16 v[30:33], v[146:149], v[224:227], v[118:121]
	v_mfma_f32_16x16x32_bf16 v[22:25], v[154:157], v[162:165], v[22:25]
	v_mfma_f32_16x16x32_bf16 v[18:21], v[154:157], v[196:199], v[18:21]
	v_mfma_f32_16x16x32_bf16 v[14:17], v[154:157], v[204:207], v[14:17]
	v_mfma_f32_16x16x32_bf16 v[126:129], v[150:153], v[228:231], v[30:33]
	v_mfma_f32_16x16x32_bf16 v[30:33], v[154:157], v[224:227], v[58:61]
	v_mfma_f32_16x16x32_bf16 v[22:25], v[158:161], v[166:169], v[22:25]
	v_mfma_f32_16x16x32_bf16 v[18:21], v[158:161], v[200:203], v[18:21]
	v_mfma_f32_16x16x32_bf16 v[14:17], v[158:161], v[208:211], v[14:17]
	v_mfma_f32_16x16x32_bf16 v[58:61], v[158:161], v[228:231], v[30:33]
	s_barrier
	s_add_i32 s93, s93, 2
	s_add_u32 s8, s8, 0x100
	s_addc_u32 s9, s9, 0
	s_add_u32 s91, s91, 0x100
	s_addc_u32 s92, s92, 0
	s_cmp_gt_u32 s93, 13

.LBB0_1462:
	s_add_u32 s16, s16, 0xb0080
	s_addc_u32 s17, s17, 0
	s_add_u32 s43, s18, 0x100
	s_addc_u32 s44, s19, 0
	s_mov_b32 s45, -2
	ds_read_b128 v[128:131], v169
	ds_read_b128 v[132:135], v169 offset:1024
	ds_read_b128 v[136:139], v169 offset:2048
	ds_read_b128 v[140:143], v169 offset:3072
	ds_read_b128 v[160:163], v170
	ds_read_b128 v[172:175], v170 offset:1024
	ds_read_b128 v[176:179], v170 offset:2048
	ds_read_b128 v[180:183], v170 offset:3072
	s_add_u32 s18, s16, 0xfff50080
	s_addc_u32 s19, s17, -1
	s_cmp_eq_u32 s45, 40
	s_cselect_b32 s21, s5, s19
	s_cselect_b32 s20, s4, s18
	s_cselect_b32 s19, s15, s44
	s_cselect_b32 s18, s14, s43
	s_add_i32 m0, s26, 0xc000
	ds_read_b128 v[184:187], v171
	ds_read_b128 v[188:191], v171 offset:1024
	ds_read_b128 v[192:195], v171 offset:2048
	ds_read_b128 v[196:199], v171 offset:3072
	ds_read_b128 v[200:203], v171 offset:4096
	ds_read_b128 v[204:207], v171 offset:5120
	ds_read_b128 v[208:211], v171 offset:6144
	ds_read_b128 v[212:215], v171 offset:7168
	global_load_lds_dwordx4 v152, s[16:17]
	s_add_i32 m0, s26, 0xe000
	s_nop 0
	global_load_lds_dwordx4 v154, s[16:17]
	s_waitcnt vmcnt(8) lgkmcnt(0)
	s_barrier
	v_mfma_f32_16x16x32_bf16 v[124:127], v[128:131], v[184:187], 0
	v_mfma_f32_16x16x32_bf16 v[120:123], v[136:139], v[184:187], 0
	v_mfma_f32_16x16x32_bf16 v[116:119], v[128:131], v[192:195], 0
	v_mfma_f32_16x16x32_bf16 v[108:111], v[136:139], v[192:195], 0
	v_mfma_f32_16x16x32_bf16 v[92:95], v[128:131], v[200:203], 0
	v_mfma_f32_16x16x32_bf16 v[88:91], v[136:139], v[200:203], 0
	v_mfma_f32_16x16x32_bf16 v[84:87], v[128:131], v[208:211], 0
	v_mfma_f32_16x16x32_bf16 v[80:83], v[136:139], v[208:211], 0
	v_mfma_f32_16x16x32_bf16 v[124:127], v[132:135], v[188:191], v[124:127]
	v_mfma_f32_16x16x32_bf16 v[120:123], v[140:143], v[188:191], v[120:123]
	v_mfma_f32_16x16x32_bf16 v[116:119], v[132:135], v[196:199], v[116:119]
	v_mfma_f32_16x16x32_bf16 v[108:111], v[140:143], v[196:199], v[108:111]
	v_mfma_f32_16x16x32_bf16 v[92:95], v[132:135], v[204:207], v[92:95]
	v_mfma_f32_16x16x32_bf16 v[88:91], v[140:143], v[204:207], v[88:91]
	v_mfma_f32_16x16x32_bf16 v[84:87], v[132:135], v[212:215], v[84:87]
	v_mfma_f32_16x16x32_bf16 v[80:83], v[140:143], v[212:215], v[80:83]
	v_mfma_f32_16x16x32_bf16 v[112:115], v[160:163], v[184:187], 0
	v_mfma_f32_16x16x32_bf16 v[104:107], v[176:179], v[184:187], 0
	v_mfma_f32_16x16x32_bf16 v[100:103], v[160:163], v[192:195], 0
	v_mfma_f32_16x16x32_bf16 v[96:99], v[176:179], v[192:195], 0
	v_mfma_f32_16x16x32_bf16 v[76:79], v[160:163], v[200:203], 0
	v_mfma_f32_16x16x32_bf16 v[72:75], v[176:179], v[200:203], 0
	v_mfma_f32_16x16x32_bf16 v[68:71], v[160:163], v[208:211], 0
	v_mfma_f32_16x16x32_bf16 v[64:67], v[176:179], v[208:211], 0
	v_mfma_f32_16x16x32_bf16 v[112:115], v[172:175], v[188:191], v[112:115]
	v_mfma_f32_16x16x32_bf16 v[104:107], v[180:183], v[188:191], v[104:107]
	v_mfma_f32_16x16x32_bf16 v[100:103], v[172:175], v[196:199], v[100:103]
	v_mfma_f32_16x16x32_bf16 v[96:99], v[180:183], v[196:199], v[96:99]
	v_mfma_f32_16x16x32_bf16 v[76:79], v[172:175], v[204:207], v[76:79]
	v_mfma_f32_16x16x32_bf16 v[72:75], v[180:183], v[204:207], v[72:75]
	v_mfma_f32_16x16x32_bf16 v[68:71], v[172:175], v[212:215], v[68:71]
	v_mfma_f32_16x16x32_bf16 v[64:67], v[180:183], v[212:215], v[64:67]
	s_barrier
	s_add_u32 s98, s18, 0x80
	s_addc_u32 s99, s19, 0
	s_add_u32 s100, s20, 0x80
	s_addc_u32 s101, s21, 0
	s_add_i32 s46, s37, s25
	s_mov_b32 m0, s46
	ds_read_b128 v[184:187], v171 offset:16384
	ds_read_b128 v[188:191], v171 offset:17408
	ds_read_b128 v[192:195], v171 offset:18432
	ds_read_b128 v[196:199], v171 offset:19456
	ds_read_b128 v[200:203], v171 offset:20480
	ds_read_b128 v[204:207], v171 offset:21504
	ds_read_b128 v[208:211], v171 offset:22528
	ds_read_b128 v[212:215], v171 offset:23552
	s_cmp_eq_u32 s45, 40
	s_cselect_b64 exec, 0, -1
	s_cmp_lg_u32 s33, 0x100
	s_cselect_b64 exec, -1, exec
	global_load_lds_dwordx4 v146, s[18:19]
	s_add_i32 m0, s46, 0x2000
	s_add_u32 s46, s18, 0xb0000
	s_addc_u32 s47, s19, 0
	s_add_i32 s48, s38, s25
	global_load_lds_dwordx4 v150, s[18:19]
	s_mov_b32 m0, s48
	s_nop 0
	global_load_lds_dwordx4 v146, s[46:47]
	s_add_i32 m0, s48, 0x2000
	s_nop 0
	global_load_lds_dwordx4 v150, s[46:47]
	s_mov_b32 m0, s26
	s_nop 0
	global_load_lds_dwordx4 v144, s[20:21]
	s_mov_b32 m0, s27
	s_nop 0
	global_load_lds_dwordx4 v148, s[20:21]
	s_mov_b64 exec, -1
	s_waitcnt vmcnt(8) lgkmcnt(0)
	s_barrier
	v_mfma_f32_16x16x32_bf16 v[60:63], v[128:131], v[184:187], 0
	v_mfma_f32_16x16x32_bf16 v[56:59], v[136:139], v[184:187], 0
	v_mfma_f32_16x16x32_bf16 v[52:55], v[128:131], v[192:195], 0
	v_mfma_f32_16x16x32_bf16 v[48:51], v[136:139], v[192:195], 0
	v_mfma_f32_16x16x32_bf16 v[28:31], v[128:131], v[200:203], 0
	v_mfma_f32_16x16x32_bf16 v[24:27], v[136:139], v[200:203], 0
	v_mfma_f32_16x16x32_bf16 v[20:23], v[128:131], v[208:211], 0
	v_mfma_f32_16x16x32_bf16 v[16:19], v[136:139], v[208:211], 0
	v_mfma_f32_16x16x32_bf16 v[60:63], v[132:135], v[188:191], v[60:63]
	v_mfma_f32_16x16x32_bf16 v[56:59], v[140:143], v[188:191], v[56:59]
	v_mfma_f32_16x16x32_bf16 v[52:55], v[132:135], v[196:199], v[52:55]
	v_mfma_f32_16x16x32_bf16 v[48:51], v[140:143], v[196:199], v[48:51]
	v_mfma_f32_16x16x32_bf16 v[28:31], v[132:135], v[204:207], v[28:31]
	v_mfma_f32_16x16x32_bf16 v[24:27], v[140:143], v[204:207], v[24:27]
	v_mfma_f32_16x16x32_bf16 v[20:23], v[132:135], v[212:215], v[20:23]
	v_mfma_f32_16x16x32_bf16 v[16:19], v[140:143], v[212:215], v[16:19]
	v_mfma_f32_16x16x32_bf16 v[44:47], v[160:163], v[184:187], 0
	v_mfma_f32_16x16x32_bf16 v[40:43], v[176:179], v[184:187], 0
	v_mfma_f32_16x16x32_bf16 v[36:39], v[160:163], v[192:195], 0
	v_mfma_f32_16x16x32_bf16 v[32:35], v[176:179], v[192:195], 0
	v_mfma_f32_16x16x32_bf16 v[12:15], v[160:163], v[200:203], 0
	v_mfma_f32_16x16x32_bf16 v[8:11], v[176:179], v[200:203], 0
	v_mfma_f32_16x16x32_bf16 v[4:7], v[160:163], v[208:211], 0
	v_mfma_f32_16x16x32_bf16 v[0:3], v[176:179], v[208:211], 0
	v_mfma_f32_16x16x32_bf16 v[44:47], v[172:175], v[188:191], v[44:47]
	v_mfma_f32_16x16x32_bf16 v[40:43], v[180:183], v[188:191], v[40:43]
	v_mfma_f32_16x16x32_bf16 v[36:39], v[172:175], v[196:199], v[36:39]
	v_mfma_f32_16x16x32_bf16 v[32:35], v[180:183], v[196:199], v[32:35]
	v_mfma_f32_16x16x32_bf16 v[12:15], v[172:175], v[204:207], v[12:15]
	v_mfma_f32_16x16x32_bf16 v[8:11], v[180:183], v[204:207], v[8:11]
	v_mfma_f32_16x16x32_bf16 v[4:7], v[172:175], v[212:215], v[4:7]
	v_mfma_f32_16x16x32_bf16 v[0:3], v[180:183], v[212:215], v[0:3]
	s_barrier
	s_add_i32 s46, 0, 0x18000
	s_add_i32 s47, 0, 0x1c000
	v_add_u32_e32 v140, s46, v167
	v_add_u32_e32 v180, s47, v167
	ds_read_b128 v[128:131], v140
	ds_read_b128 v[132:135], v140 offset:1024
	ds_read_b128 v[136:139], v140 offset:2048
	ds_read_b128 v[140:143], v140 offset:3072
	ds_read_b128 v[160:163], v180
	ds_read_b128 v[172:175], v180 offset:1024
	ds_read_b128 v[176:179], v180 offset:2048
	ds_read_b128 v[180:183], v180 offset:3072
	s_add_u32 s20, s20, 0xb0000
	s_addc_u32 s21, s21, 0
	s_mov_b32 m0, s28
	ds_read_b128 v[184:187], v171 offset:32768
	ds_read_b128 v[188:191], v171 offset:33792
	ds_read_b128 v[192:195], v171 offset:34816
	ds_read_b128 v[196:199], v171 offset:35840
	ds_read_b128 v[200:203], v171 offset:36864
	ds_read_b128 v[204:207], v171 offset:37888
	ds_read_b128 v[208:211], v171 offset:38912
	ds_read_b128 v[212:215], v171 offset:39936
	s_cmp_eq_u32 s45, 40
	s_cselect_b64 exec, 0, -1
	s_cmp_lg_u32 s33, 0x100
	s_cselect_b64 exec, -1, exec
	global_load_lds_dwordx4 v144, s[20:21]
	s_mov_b32 m0, s29
	s_nop 0
	global_load_lds_dwordx4 v148, s[20:21]
	s_mov_b64 exec, -1
	s_waitcnt vmcnt(8) lgkmcnt(0)
	s_barrier
	v_mfma_f32_16x16x32_bf16 v[124:127], v[128:131], v[184:187], v[124:127]
	v_mfma_f32_16x16x32_bf16 v[120:123], v[136:139], v[184:187], v[120:123]
	v_mfma_f32_16x16x32_bf16 v[116:119], v[128:131], v[192:195], v[116:119]
	v_mfma_f32_16x16x32_bf16 v[108:111], v[136:139], v[192:195], v[108:111]
	v_mfma_f32_16x16x32_bf16 v[92:95], v[128:131], v[200:203], v[92:95]
	v_mfma_f32_16x16x32_bf16 v[88:91], v[136:139], v[200:203], v[88:91]
	v_mfma_f32_16x16x32_bf16 v[84:87], v[128:131], v[208:211], v[84:87]
	v_mfma_f32_16x16x32_bf16 v[80:83], v[136:139], v[208:211], v[80:83]
	v_mfma_f32_16x16x32_bf16 v[124:127], v[132:135], v[188:191], v[124:127]
	v_mfma_f32_16x16x32_bf16 v[120:123], v[140:143], v[188:191], v[120:123]
	v_mfma_f32_16x16x32_bf16 v[116:119], v[132:135], v[196:199], v[116:119]
	v_mfma_f32_16x16x32_bf16 v[108:111], v[140:143], v[196:199], v[108:111]
	v_mfma_f32_16x16x32_bf16 v[92:95], v[132:135], v[204:207], v[92:95]
	v_mfma_f32_16x16x32_bf16 v[88:91], v[140:143], v[204:207], v[88:91]
	v_mfma_f32_16x16x32_bf16 v[84:87], v[132:135], v[212:215], v[84:87]
	v_mfma_f32_16x16x32_bf16 v[80:83], v[140:143], v[212:215], v[80:83]
	v_mfma_f32_16x16x32_bf16 v[112:115], v[160:163], v[184:187], v[112:115]
	v_mfma_f32_16x16x32_bf16 v[104:107], v[176:179], v[184:187], v[104:107]
	v_mfma_f32_16x16x32_bf16 v[100:103], v[160:163], v[192:195], v[100:103]
	v_mfma_f32_16x16x32_bf16 v[96:99], v[176:179], v[192:195], v[96:99]
	v_mfma_f32_16x16x32_bf16 v[76:79], v[160:163], v[200:203], v[76:79]
	v_mfma_f32_16x16x32_bf16 v[72:75], v[176:179], v[200:203], v[72:75]
	v_mfma_f32_16x16x32_bf16 v[68:71], v[160:163], v[208:211], v[68:71]
	v_mfma_f32_16x16x32_bf16 v[64:67], v[176:179], v[208:211], v[64:67]
	v_mfma_f32_16x16x32_bf16 v[112:115], v[172:175], v[188:191], v[112:115]
	v_mfma_f32_16x16x32_bf16 v[104:107], v[180:183], v[188:191], v[104:107]
	v_mfma_f32_16x16x32_bf16 v[100:103], v[172:175], v[196:199], v[100:103]
	v_mfma_f32_16x16x32_bf16 v[96:99], v[180:183], v[196:199], v[96:99]
	v_mfma_f32_16x16x32_bf16 v[76:79], v[172:175], v[204:207], v[76:79]
	v_mfma_f32_16x16x32_bf16 v[72:75], v[180:183], v[204:207], v[72:75]
	v_mfma_f32_16x16x32_bf16 v[68:71], v[172:175], v[212:215], v[68:71]
	v_mfma_f32_16x16x32_bf16 v[64:67], v[180:183], v[212:215], v[64:67]
	s_barrier
	s_add_i32 s20, s46, s25
	s_mov_b32 m0, s20
	ds_read_b128 v[184:187], v171 offset:49152
	ds_read_b128 v[188:191], v171 offset:50176
	ds_read_b128 v[192:195], v171 offset:51200
	ds_read_b128 v[196:199], v171 offset:52224
	ds_read_b128 v[200:203], v171 offset:53248
	ds_read_b128 v[204:207], v171 offset:54272
	ds_read_b128 v[208:211], v171 offset:55296
	ds_read_b128 v[212:215], v171 offset:56320
	s_cmp_eq_u32 s45, 40
	s_cselect_b64 exec, 0, -1
	s_cmp_lg_u32 s33, 0x100
	s_cselect_b64 exec, -1, exec
	global_load_lds_dwordx4 v146, s[98:99]
	s_add_i32 m0, s20, 0x2000
	s_add_u32 s18, s18, 0xb0080
	s_addc_u32 s19, s19, 0
	s_add_i32 s20, s47, s25
	global_load_lds_dwordx4 v150, s[98:99]
	s_mov_b32 m0, s20
	s_nop 0
	global_load_lds_dwordx4 v146, s[18:19]
	s_add_i32 m0, s20, 0x2000
	s_nop 0
	global_load_lds_dwordx4 v150, s[18:19]
	s_mov_b32 m0, s35
	s_nop 0
	global_load_lds_dwordx4 v144, s[100:101]
	s_mov_b32 m0, s36
	s_nop 0
	global_load_lds_dwordx4 v148, s[100:101]
	s_mov_b64 exec, -1
	s_waitcnt vmcnt(8) lgkmcnt(0)
	s_barrier
	v_mfma_f32_16x16x32_bf16 v[60:63], v[128:131], v[184:187], v[60:63]
	v_mfma_f32_16x16x32_bf16 v[56:59], v[136:139], v[184:187], v[56:59]
	v_mfma_f32_16x16x32_bf16 v[52:55], v[128:131], v[192:195], v[52:55]
	v_mfma_f32_16x16x32_bf16 v[48:51], v[136:139], v[192:195], v[48:51]
	v_mfma_f32_16x16x32_bf16 v[28:31], v[128:131], v[200:203], v[28:31]
	v_mfma_f32_16x16x32_bf16 v[24:27], v[136:139], v[200:203], v[24:27]
	v_mfma_f32_16x16x32_bf16 v[20:23], v[128:131], v[208:211], v[20:23]
	v_mfma_f32_16x16x32_bf16 v[16:19], v[136:139], v[208:211], v[16:19]
	v_mfma_f32_16x16x32_bf16 v[60:63], v[132:135], v[188:191], v[60:63]
	v_mfma_f32_16x16x32_bf16 v[56:59], v[140:143], v[188:191], v[56:59]
	v_mfma_f32_16x16x32_bf16 v[52:55], v[132:135], v[196:199], v[52:55]
	v_mfma_f32_16x16x32_bf16 v[48:51], v[140:143], v[196:199], v[48:51]
	v_mfma_f32_16x16x32_bf16 v[28:31], v[132:135], v[204:207], v[28:31]
	v_mfma_f32_16x16x32_bf16 v[24:27], v[140:143], v[204:207], v[24:27]
	v_mfma_f32_16x16x32_bf16 v[20:23], v[132:135], v[212:215], v[20:23]
	v_mfma_f32_16x16x32_bf16 v[16:19], v[140:143], v[212:215], v[16:19]
	v_mfma_f32_16x16x32_bf16 v[44:47], v[160:163], v[184:187], v[44:47]
	v_mfma_f32_16x16x32_bf16 v[40:43], v[176:179], v[184:187], v[40:43]
	v_mfma_f32_16x16x32_bf16 v[36:39], v[160:163], v[192:195], v[36:39]
	v_mfma_f32_16x16x32_bf16 v[32:35], v[176:179], v[192:195], v[32:35]
	v_mfma_f32_16x16x32_bf16 v[12:15], v[160:163], v[200:203], v[12:15]
	v_mfma_f32_16x16x32_bf16 v[8:11], v[176:179], v[200:203], v[8:11]
	v_mfma_f32_16x16x32_bf16 v[4:7], v[160:163], v[208:211], v[4:7]
	v_mfma_f32_16x16x32_bf16 v[0:3], v[176:179], v[208:211], v[0:3]
	v_mfma_f32_16x16x32_bf16 v[44:47], v[172:175], v[188:191], v[44:47]
	v_mfma_f32_16x16x32_bf16 v[40:43], v[180:183], v[188:191], v[40:43]
	v_mfma_f32_16x16x32_bf16 v[36:39], v[172:175], v[196:199], v[36:39]
	v_mfma_f32_16x16x32_bf16 v[32:35], v[180:183], v[196:199], v[32:35]
	v_mfma_f32_16x16x32_bf16 v[12:15], v[172:175], v[204:207], v[12:15]
	v_mfma_f32_16x16x32_bf16 v[8:11], v[180:183], v[204:207], v[8:11]
	v_mfma_f32_16x16x32_bf16 v[4:7], v[172:175], v[212:215], v[4:7]
	v_mfma_f32_16x16x32_bf16 v[0:3], v[180:183], v[212:215], v[0:3]
	s_barrier
	s_add_i32 s45, s45, 2
	s_add_u32 s16, s16, 0x100
	s_addc_u32 s17, s17, 0
	s_add_u32 s43, s43, 0x100
	s_addc_u32 s44, s44, 0
	s_cmp_gt_u32 s45, 41
